# store widening (7.3): P5 epilogue keeps the n=0 packed results in registers and stores ACT as 16 dwordx4 per wave instead of 32 dwordx2
# speedup vs baseline: 1.0115x; 1.0115x over previous
; __device__ __forceinline__ float row_rstd(const float* ssp, int row, int fq) {
;     const f32x4 a = *(const f32x4*)(ssp + (size_t)row * 32 + 8 * fq), b = *(const f32x4*)(ssp + (size_t)row * 32 + 8 * fq + 4);
;     float s = ((a[0] + a[1]) + (a[2] + a[3])) + ((b[0] + b[1]) + (b[2] + b[3]));
;     s += __shfl_xor(s, 16); s += __shfl_xor(s, 32);
;     return __builtin_amdgcn_rsqf(s * (1.0f / 2048.0f) + 1e-6f);
;     __device__ __forceinline__ void operator()(f32x4 (&acc)[2][2][4][2], const Unit& u, int wr, int wc, int fr, int fq) const {
;         const int row0 = u.pm * BM + wr * 64 + fr;
; #pragma unroll
;         for (int ai = 0; ai < 2; ++ai)
; #pragma unroll
;             for (int m = 0; m < 4; ++m) { const float rstd = row_rstd(ss, row0 + ai * HALF + m * 16, fq);
; #pragma unroll
;                 for (int bj = 0; bj < 2; ++bj) { acc[ai][bj][m][0] *= rstd; acc[ai][bj][m][1] *= rstd; } }
; #pragma unroll
;         for (int n = 0; n < 2; ++n) {
;             const int j4 = u.pn * 128 + wc * 32 + 8 * fq + 4 * n;
;             f32x4 kc[2][3], bc[2];
; #pragma unroll
;             for (int bj = 0; bj < 2; ++bj) { bc[bj] = *(const f32x4*)(cb + bj * FF + j4);
; #pragma unroll
;                 for (int w = 0; w < 3; ++w) kc[bj][w] = *(const f32x4*)(ck + w * NUP + bj * FF + j4); }
.LBB0_755:
	s_waitcnt vmcnt(14)
	v_add_f32_e32 v174, v174, v175
	v_add_f32_e32 v176, v176, v177
	v_add_f32_e32 v178, v178, v179
	v_add_f32_e32 v180, v180, v181
	v_add_f32_e32 v174, v174, v176
	v_add_f32_e32 v178, v178, v180
	v_add_f32_e32 v130, v174, v178
	s_waitcnt vmcnt(12)
	v_add_f32_e32 v182, v182, v183
	v_add_f32_e32 v184, v184, v185
	v_add_f32_e32 v186, v186, v187
	v_add_f32_e32 v188, v188, v189
	v_add_f32_e32 v182, v182, v184
	v_add_f32_e32 v186, v186, v188
	v_add_f32_e32 v132, v182, v186
	s_waitcnt vmcnt(10)
	v_add_f32_e32 v190, v190, v191
	v_add_f32_e32 v192, v192, v193
	v_add_f32_e32 v194, v194, v195
	v_add_f32_e32 v196, v196, v197
	v_add_f32_e32 v190, v190, v192
	v_add_f32_e32 v194, v194, v196
	v_add_f32_e32 v134, v190, v194
	s_waitcnt vmcnt(8)
	v_add_f32_e32 v198, v198, v199
	v_add_f32_e32 v200, v200, v201
	v_add_f32_e32 v202, v202, v203
	v_add_f32_e32 v204, v204, v205
	v_add_f32_e32 v198, v198, v200
	v_add_f32_e32 v202, v202, v204
	v_add_f32_e32 v136, v198, v202
	s_waitcnt vmcnt(6)
	v_add_f32_e32 v206, v206, v207
	v_add_f32_e32 v208, v208, v209
	v_add_f32_e32 v210, v210, v211
	v_add_f32_e32 v212, v212, v213
	v_add_f32_e32 v206, v206, v208
	v_add_f32_e32 v210, v210, v212
	v_add_f32_e32 v138, v206, v210
	s_waitcnt vmcnt(4)
	v_add_f32_e32 v214, v214, v215
	v_add_f32_e32 v216, v216, v217
	v_add_f32_e32 v218, v218, v219
	v_add_f32_e32 v220, v220, v221
	v_add_f32_e32 v214, v214, v216
	v_add_f32_e32 v218, v218, v220
	v_add_f32_e32 v140, v214, v218
	s_waitcnt vmcnt(2)
	v_add_f32_e32 v222, v222, v223
	v_add_f32_e32 v224, v224, v225
	v_add_f32_e32 v226, v226, v227
	v_add_f32_e32 v228, v228, v229
	v_add_f32_e32 v222, v222, v224
	v_add_f32_e32 v226, v226, v228
	v_add_f32_e32 v142, v222, v226
	s_waitcnt vmcnt(0)
	v_add_f32_e32 v230, v230, v231
	v_add_f32_e32 v232, v232, v233
	v_add_f32_e32 v234, v234, v235
	v_add_f32_e32 v236, v236, v237
	v_add_f32_e32 v230, v230, v232
	v_add_f32_e32 v234, v234, v236
	v_add_f32_e32 v144, v230, v234
	v_lshl_or_b32 v242, s16, 7, v250
	v_lshlrev_b32_e32 v252, 1, v242
	v_lshlrev_b32_e32 v242, 2, v242
	v_add_u32_e32 v131, 0x5600, v242
	v_add_u32_e32 v133, 0xac00, v242
	v_add_u32_e32 v135, 0x10200, v242
	v_add_u32_e32 v137, 0x15800, v242
	v_add_u32_e32 v139, 0x1ae00, v242
	global_load_dwordx4 v[182:185], v242, s[18:19]
	global_load_dwordx4 v[186:189], v133, s[18:19]
	global_load_dwordx4 v[190:193], v137, s[18:19]
	global_load_dwordx4 v[194:197], v242, s[20:21]
	global_load_dwordx4 v[198:201], v131, s[18:19]
	global_load_dwordx4 v[202:205], v135, s[18:19]
	global_load_dwordx4 v[206:209], v139, s[18:19]
	global_load_dwordx4 v[210:213], v131, s[20:21]
	ds_bpermute_b32 v174, v238, v130
	ds_bpermute_b32 v175, v238, v132
	ds_bpermute_b32 v176, v238, v134
	ds_bpermute_b32 v177, v238, v136
	ds_bpermute_b32 v178, v238, v138
	ds_bpermute_b32 v179, v238, v140
	ds_bpermute_b32 v180, v238, v142
	ds_bpermute_b32 v181, v238, v144
	s_waitcnt lgkmcnt(0)
	v_add_f32_e32 v130, v130, v174
	v_add_f32_e32 v132, v132, v175
	v_add_f32_e32 v134, v134, v176
	v_add_f32_e32 v136, v136, v177
	v_add_f32_e32 v138, v138, v178
	v_add_f32_e32 v140, v140, v179
	v_add_f32_e32 v142, v142, v180
	v_add_f32_e32 v144, v144, v181
	ds_bpermute_b32 v174, v239, v130
	ds_bpermute_b32 v175, v239, v132
	ds_bpermute_b32 v176, v239, v134
	ds_bpermute_b32 v177, v239, v136
	ds_bpermute_b32 v178, v239, v138
	ds_bpermute_b32 v179, v239, v140
	ds_bpermute_b32 v180, v239, v142
	ds_bpermute_b32 v181, v239, v144
	s_waitcnt lgkmcnt(0)
	v_add_f32_e32 v130, v130, v174
	v_add_f32_e32 v132, v132, v175
	v_add_f32_e32 v134, v134, v176
	v_add_f32_e32 v136, v136, v177
	v_add_f32_e32 v138, v138, v178
	v_add_f32_e32 v140, v140, v179
	v_add_f32_e32 v142, v142, v180
	v_add_f32_e32 v144, v144, v181
	v_fmamk_f32 v130, v130, 0x3a000000, v243
	v_fmamk_f32 v132, v132, 0x3a000000, v243
	v_fmamk_f32 v134, v134, 0x3a000000, v243
	v_fmamk_f32 v136, v136, 0x3a000000, v243
	v_fmamk_f32 v138, v138, 0x3a000000, v243
	v_fmamk_f32 v140, v140, 0x3a000000, v243
	v_fmamk_f32 v142, v142, 0x3a000000, v243
	v_fmamk_f32 v144, v144, 0x3a000000, v243
	v_rsq_f32_e32 v130, v130
	v_rsq_f32_e32 v132, v132
	v_rsq_f32_e32 v134, v134
	v_rsq_f32_e32 v136, v136
	v_rsq_f32_e32 v138, v138
	v_rsq_f32_e32 v140, v140
	v_rsq_f32_e32 v142, v142
	v_rsq_f32_e32 v144, v144
	s_nop 0
	v_pk_mul_f32 v[126:127], v[126:127], v[130:131] op_sel_hi:[1,0]
	v_pk_mul_f32 v[128:129], v[128:129], v[130:131] op_sel_hi:[1,0]
	v_pk_mul_f32 v[62:63], v[62:63], v[130:131] op_sel_hi:[1,0]
	v_pk_mul_f32 v[64:65], v[64:65], v[130:131] op_sel_hi:[1,0]
	v_pk_mul_f32 v[122:123], v[122:123], v[130:131] op_sel_hi:[1,0]
	v_pk_mul_f32 v[124:125], v[124:125], v[130:131] op_sel_hi:[1,0]
	v_pk_mul_f32 v[54:55], v[54:55], v[130:131] op_sel_hi:[1,0]
	v_pk_mul_f32 v[56:57], v[56:57], v[130:131] op_sel_hi:[1,0]
	v_pk_mul_f32 v[118:119], v[118:119], v[132:133] op_sel_hi:[1,0]
	v_pk_mul_f32 v[120:121], v[120:121], v[132:133] op_sel_hi:[1,0]
	v_pk_mul_f32 v[58:59], v[58:59], v[132:133] op_sel_hi:[1,0]
	v_pk_mul_f32 v[60:61], v[60:61], v[132:133] op_sel_hi:[1,0]
	v_pk_mul_f32 v[114:115], v[114:115], v[132:133] op_sel_hi:[1,0]
	v_pk_mul_f32 v[116:117], v[116:117], v[132:133] op_sel_hi:[1,0]
	v_pk_mul_f32 v[50:51], v[50:51], v[132:133] op_sel_hi:[1,0]
	v_pk_mul_f32 v[52:53], v[52:53], v[132:133] op_sel_hi:[1,0]
	v_pk_mul_f32 v[110:111], v[110:111], v[134:135] op_sel_hi:[1,0]
	v_pk_mul_f32 v[112:113], v[112:113], v[134:135] op_sel_hi:[1,0]
	v_pk_mul_f32 v[46:47], v[46:47], v[134:135] op_sel_hi:[1,0]
	v_pk_mul_f32 v[48:49], v[48:49], v[134:135] op_sel_hi:[1,0]
	v_pk_mul_f32 v[102:103], v[102:103], v[134:135] op_sel_hi:[1,0]
	v_pk_mul_f32 v[104:105], v[104:105], v[134:135] op_sel_hi:[1,0]
; __device__ __forceinline__ float sigmoid_f(float x) { return fast_rcp(1.0f + fast_exp2(-1.4426950409f * x)); }
;     __device__ __forceinline__ void operator()(f32x4 (&acc)[2][2][4][2], const Unit& u, int wr, int wc, int fr, int fq) const {
;     ...
;                 for (int bj = 0; bj < 2; ++bj) { acc[ai][bj][m][0] *= rstd; acc[ai][bj][m][1] *= rstd; } }
; #pragma unroll
;         for (int n = 0; n < 2; ++n) {
;             const int j4 = u.pn * 128 + wc * 32 + 8 * fq + 4 * n;
;             f32x4 kc[2][3], bc[2];
; #pragma unroll
;             for (int bj = 0; bj < 2; ++bj) { bc[bj] = *(const f32x4*)(cb + bj * FF + j4);
; #pragma unroll
;                 for (int w = 0; w < 3; ++w) kc[bj][w] = *(const f32x4*)(ck + w * NUP + bj * FF + j4); }
; #pragma unroll
;             for (int ai = 0; ai < 2; ++ai) {
;                 const int grp = u.pm * 4 + ai * 2 + wr;
; #pragma unroll
;                 for (int m = 0; m < 4; ++m) {
;                     f32x4 cv[2];
; #pragma unroll
;                     for (int bj = 0; bj < 2; ++bj) {
;                         const f32x4 cur = acc[ai][bj][m][n], lo = acc[ai][bj][m > 0 ? m - 1 : 0][n], hi = acc[ai][bj][m < 3 ? m + 1 : 3][n];
;                         f32x4 pv, nv;
; #pragma unroll
;                         for (int idx = 0; idx < 4; ++idx) {
;                             const float y = (fr == 15) ? lo[idx] : cur[idx], z = (fr == 0) ? hi[idx] : cur[idx];
;                             pv[idx] = __int_as_float(__builtin_amdgcn_update_dpp(0, __float_as_int(y), 0x121, 0xf, 0xf, false));
;                             nv[idx] = __int_as_float(__builtin_amdgcn_update_dpp(0, __float_as_int(z), 0x12f, 0xf, 0xf, false));
;                         }
;                         cv[bj] = kc[bj][0] * pv + kc[bj][1] * cur + kc[bj][2] * nv + bc[bj];
;                     }
;                     const int row = row0 + ai * HALF + m * 16;
;                     const bool edge = (m == 0 && fr == 0) || (m == 3 && fr == 15);
;                     if (!edge) { const f32x4 gt = cv[0], vl = cv[1];
;                         u32x2 w; w.x = cvt_pk_bf16(gt[0] * sigmoid_f(gt[0]) * vl[0], gt[1] * sigmoid_f(gt[1]) * vl[1]); w.y = cvt_pk_bf16(gt[2] * sigmoid_f(gt[2]) * vl[2], gt[3] * sigmoid_f(gt[3]) * vl[3]);
;                         *(u32x2*)(ACT + (size_t)row * FF + j4) = w; }
;                     if (m == 0 && fr < 2) {
; #pragma unroll
	v_pk_mul_f32 v[38:39], v[38:39], v[134:135] op_sel_hi:[1,0]
	v_pk_mul_f32 v[40:41], v[40:41], v[134:135] op_sel_hi:[1,0]
	v_pk_mul_f32 v[106:107], v[106:107], v[136:137] op_sel_hi:[1,0]
	v_pk_mul_f32 v[108:109], v[108:109], v[136:137] op_sel_hi:[1,0]
	v_pk_mul_f32 v[42:43], v[42:43], v[136:137] op_sel_hi:[1,0]
	v_pk_mul_f32 v[44:45], v[44:45], v[136:137] op_sel_hi:[1,0]
	v_pk_mul_f32 v[98:99], v[98:99], v[136:137] op_sel_hi:[1,0]
	v_pk_mul_f32 v[100:101], v[100:101], v[136:137] op_sel_hi:[1,0]
	v_pk_mul_f32 v[34:35], v[34:35], v[136:137] op_sel_hi:[1,0]
	v_pk_mul_f32 v[36:37], v[36:37], v[136:137] op_sel_hi:[1,0]
	v_pk_mul_f32 v[94:95], v[94:95], v[138:139] op_sel_hi:[1,0]
	v_pk_mul_f32 v[96:97], v[96:97], v[138:139] op_sel_hi:[1,0]
	v_pk_mul_f32 v[30:31], v[30:31], v[138:139] op_sel_hi:[1,0]
	v_pk_mul_f32 v[32:33], v[32:33], v[138:139] op_sel_hi:[1,0]
	v_pk_mul_f32 v[86:87], v[86:87], v[138:139] op_sel_hi:[1,0]
	v_pk_mul_f32 v[88:89], v[88:89], v[138:139] op_sel_hi:[1,0]
	v_pk_mul_f32 v[22:23], v[22:23], v[138:139] op_sel_hi:[1,0]
	v_pk_mul_f32 v[24:25], v[24:25], v[138:139] op_sel_hi:[1,0]
	v_pk_mul_f32 v[90:91], v[90:91], v[140:141] op_sel_hi:[1,0]
	v_pk_mul_f32 v[92:93], v[92:93], v[140:141] op_sel_hi:[1,0]
	v_pk_mul_f32 v[26:27], v[26:27], v[140:141] op_sel_hi:[1,0]
	v_pk_mul_f32 v[28:29], v[28:29], v[140:141] op_sel_hi:[1,0]
	v_pk_mul_f32 v[82:83], v[82:83], v[140:141] op_sel_hi:[1,0]
	v_pk_mul_f32 v[84:85], v[84:85], v[140:141] op_sel_hi:[1,0]
	v_pk_mul_f32 v[18:19], v[18:19], v[140:141] op_sel_hi:[1,0]
	v_pk_mul_f32 v[20:21], v[20:21], v[140:141] op_sel_hi:[1,0]
	v_pk_mul_f32 v[78:79], v[78:79], v[142:143] op_sel_hi:[1,0]
	v_pk_mul_f32 v[80:81], v[80:81], v[142:143] op_sel_hi:[1,0]
	v_pk_mul_f32 v[14:15], v[14:15], v[142:143] op_sel_hi:[1,0]
	v_pk_mul_f32 v[16:17], v[16:17], v[142:143] op_sel_hi:[1,0]
	v_pk_mul_f32 v[70:71], v[70:71], v[142:143] op_sel_hi:[1,0]
	v_pk_mul_f32 v[72:73], v[72:73], v[142:143] op_sel_hi:[1,0]
	v_pk_mul_f32 v[6:7], v[6:7], v[142:143] op_sel_hi:[1,0]
	v_pk_mul_f32 v[8:9], v[8:9], v[142:143] op_sel_hi:[1,0]
	v_pk_mul_f32 v[74:75], v[74:75], v[144:145] op_sel_hi:[1,0]
	v_pk_mul_f32 v[76:77], v[76:77], v[144:145] op_sel_hi:[1,0]
	v_pk_mul_f32 v[10:11], v[10:11], v[144:145] op_sel_hi:[1,0]
	v_pk_mul_f32 v[12:13], v[12:13], v[144:145] op_sel_hi:[1,0]
	v_pk_mul_f32 v[66:67], v[66:67], v[144:145] op_sel_hi:[1,0]
	v_pk_mul_f32 v[68:69], v[68:69], v[144:145] op_sel_hi:[1,0]
	v_pk_mul_f32 v[2:3], v[2:3], v[144:145] op_sel_hi:[1,0]
	v_pk_mul_f32 v[4:5], v[4:5], v[144:145] op_sel_hi:[1,0]
	s_mov_b32 s34, 0xbfb8aa3b
	s_mov_b32 s35, 0xbfb8aa3b
	s_mov_b32 s36, 1.0
	s_mov_b32 s37, 1.0
	v_lshl_add_u32 v238, s12, 8, v247
	v_mul_u32_u24_e32 v238, 0x2b00, v238
	v_add_u32_e32 v238, v238, v252
	s_lshl_b32 s13, s12, 4
	s_add_i32 s13, s13, s92
	v_add_u32_e32 v253, s13, v246
	v_mul_u32_u24_e32 v253, 0x5600, v253
	v_add_u32_e32 v253, v253, v252
	v_add_u32_e32 v239, 0x2b00, v253
	v_cvt_pk_bf16_f32 v230, v126, v127
	v_cvt_pk_bf16_f32 v231, v128, v129
	v_cvt_pk_bf16_f32 v232, v62, v63
	v_cvt_pk_bf16_f32 v233, v64, v65
	s_and_saveexec_b64 s[16:17], s[46:47]
	global_store_dwordx4 v253, v[230:233], s[54:55]
	s_or_b64 exec, exec, s[16:17]
	v_cvt_pk_bf16_f32 v234, v122, v123
	v_cvt_pk_bf16_f32 v235, v124, v125
	v_cvt_pk_bf16_f32 v236, v54, v55
	v_cvt_pk_bf16_f32 v237, v56, v57
	s_and_saveexec_b64 s[16:17], s[46:47]
	global_store_dwordx4 v239, v[234:237], s[54:55]
	s_or_b64 exec, exec, s[16:17]
	v_add_u32_e32 v253, s13, v246
	v_add_u32_e32 v253, 8, v253
	v_mul_u32_u24_e32 v253, 0x5600, v253
	v_add_u32_e32 v253, v253, v252
	v_add_u32_e32 v239, 0x2b00, v253
	v_cvt_pk_bf16_f32 v214, v94, v95
	v_cvt_pk_bf16_f32 v215, v96, v97
	v_cvt_pk_bf16_f32 v216, v30, v31
	v_cvt_pk_bf16_f32 v217, v32, v33
	s_and_saveexec_b64 s[16:17], s[46:47]
	global_store_dwordx4 v253, v[214:217], s[54:55]
	s_or_b64 exec, exec, s[16:17]
	v_cvt_pk_bf16_f32 v218, v86, v87
	v_cvt_pk_bf16_f32 v219, v88, v89
	v_cvt_pk_bf16_f32 v220, v22, v23
	v_cvt_pk_bf16_f32 v221, v24, v25
	s_and_saveexec_b64 s[16:17], s[46:47]
	global_store_dwordx4 v239, v[218:221], s[54:55]
	s_or_b64 exec, exec, s[16:17]
	v_add_u32_e32 v253, s13, v249
	v_mul_u32_u24_e32 v253, 0x5600, v253
	v_add_u32_e32 v253, v253, v252
	v_add_u32_e32 v239, 0x2b00, v253
	v_cvt_pk_bf16_f32 v230, v106, v107
	v_cvt_pk_bf16_f32 v231, v108, v109
	v_cvt_pk_bf16_f32 v232, v42, v43
	v_cvt_pk_bf16_f32 v233, v44, v45
	s_and_saveexec_b64 s[16:17], s[48:49]
	global_store_dwordx4 v253, v[230:233], s[54:55]
	s_or_b64 exec, exec, s[16:17]
	v_cvt_pk_bf16_f32 v234, v98, v99
	v_cvt_pk_bf16_f32 v235, v100, v101
	v_cvt_pk_bf16_f32 v236, v34, v35
	v_cvt_pk_bf16_f32 v237, v36, v37
	s_and_saveexec_b64 s[16:17], s[48:49]
	global_store_dwordx4 v239, v[234:237], s[54:55]
	s_or_b64 exec, exec, s[16:17]
	v_add_u32_e32 v253, s13, v249
	v_add_u32_e32 v253, 8, v253
	v_mul_u32_u24_e32 v253, 0x5600, v253
	v_add_u32_e32 v253, v253, v252
	v_add_u32_e32 v239, 0x2b00, v253
	v_cvt_pk_bf16_f32 v214, v74, v75
	v_cvt_pk_bf16_f32 v215, v76, v77
	v_cvt_pk_bf16_f32 v216, v10, v11
	v_cvt_pk_bf16_f32 v217, v12, v13
	s_and_saveexec_b64 s[16:17], s[48:49]
	global_store_dwordx4 v253, v[214:217], s[54:55]
	s_or_b64 exec, exec, s[16:17]
	v_cvt_pk_bf16_f32 v218, v66, v67
	v_cvt_pk_bf16_f32 v219, v68, v69
	v_cvt_pk_bf16_f32 v220, v2, v3
	v_cvt_pk_bf16_f32 v221, v4, v5
	s_and_saveexec_b64 s[16:17], s[48:49]
	global_store_dwordx4 v239, v[218:221], s[54:55]
	s_or_b64 exec, exec, s[16:17]
	s_waitcnt vmcnt(8)
; __device__ __forceinline__ unsigned cvt_pk_bf16(float lo, float hi) { unsigned r; asm volatile("v_cvt_pk_bf16_f32 %0, %1, %2" : "=v"(r) : "v"(lo), "v"(hi)); return r; }
; __device__ __forceinline__ float sigmoid_f(float x) { return fast_rcp(1.0f + fast_exp2(-1.4426950409f * x)); }
;     __device__ __forceinline__ void operator()(f32x4 (&acc)[2][2][4][2], const Unit& u, int wr, int wc, int fr, int fq) const {
;     ...
;                 for (int m = 0; m < 4; ++m) {
;                     f32x4 cv[2];
; #pragma unroll
;                     for (int bj = 0; bj < 2; ++bj) {
;                         const f32x4 cur = acc[ai][bj][m][n], lo = acc[ai][bj][m > 0 ? m - 1 : 0][n], hi = acc[ai][bj][m < 3 ? m + 1 : 3][n];
;                         f32x4 pv, nv;
; #pragma unroll
;                         for (int idx = 0; idx < 4; ++idx) {
;                             const float y = (fr == 15) ? lo[idx] : cur[idx], z = (fr == 0) ? hi[idx] : cur[idx];
;                             pv[idx] = __int_as_float(__builtin_amdgcn_update_dpp(0, __float_as_int(y), 0x121, 0xf, 0xf, false));
;                             nv[idx] = __int_as_float(__builtin_amdgcn_update_dpp(0, __float_as_int(z), 0x12f, 0xf, 0xf, false));
;                         }
;                         cv[bj] = kc[bj][0] * pv + kc[bj][1] * cur + kc[bj][2] * nv + bc[bj];
;                     }
;                     const int row = row0 + ai * HALF + m * 16;
;                     const bool edge = (m == 0 && fr == 0) || (m == 3 && fr == 15);
;                     if (!edge) { const f32x4 gt = cv[0], vl = cv[1];
;                         u32x2 w; w.x = cvt_pk_bf16(gt[0] * sigmoid_f(gt[0]) * vl[0], gt[1] * sigmoid_f(gt[1]) * vl[1]); w.y = cvt_pk_bf16(gt[2] * sigmoid_f(gt[2]) * vl[2], gt[3] * sigmoid_f(gt[3]) * vl[3]);
;                         *(u32x2*)(ACT + (size_t)row * FF + j4) = w; }
	v_cndmask_b32_e64 v214, 0, v182, s[42:43]
	v_cndmask_b32_e64 v215, 0, v183, s[42:43]
	v_cndmask_b32_e64 v216, 0, v184, s[42:43]
	v_cndmask_b32_e64 v217, 0, v185, s[42:43]
	v_cndmask_b32_e64 v218, 0, v198, s[42:43]
	v_cndmask_b32_e64 v219, 0, v199, s[42:43]
	v_cndmask_b32_e64 v220, 0, v200, s[42:43]
	v_cndmask_b32_e64 v221, 0, v201, s[42:43]
	v_cndmask_b32_e64 v222, 0, v190, s[38:39]
	v_cndmask_b32_e64 v223, 0, v191, s[38:39]
	v_cndmask_b32_e64 v224, 0, v192, s[38:39]
	v_cndmask_b32_e64 v225, 0, v193, s[38:39]
	v_cndmask_b32_e64 v226, 0, v206, s[38:39]
	v_cndmask_b32_e64 v227, 0, v207, s[38:39]
	v_cndmask_b32_e64 v228, 0, v208, s[38:39]
	v_cndmask_b32_e64 v229, 0, v209, s[38:39]
	v_pk_fma_f32 v[230:231], v[126:127], v[186:187], v[194:195]
	v_pk_fma_f32 v[232:233], v[128:129], v[188:189], v[196:197]
	v_pk_fma_f32 v[234:235], v[122:123], v[202:203], v[210:211]
	v_pk_fma_f32 v[236:237], v[124:125], v[204:205], v[212:213]
	v_fmac_f32_dpp v230, v126, v182 row_shr:1 row_mask:0xf bank_mask:0xf
	v_fmac_f32_dpp v231, v127, v183 row_shr:1 row_mask:0xf bank_mask:0xf
	v_fmac_f32_dpp v232, v128, v184 row_shr:1 row_mask:0xf bank_mask:0xf
	v_fmac_f32_dpp v233, v129, v185 row_shr:1 row_mask:0xf bank_mask:0xf
	v_fmac_f32_dpp v234, v122, v198 row_shr:1 row_mask:0xf bank_mask:0xf
	v_fmac_f32_dpp v235, v123, v199 row_shr:1 row_mask:0xf bank_mask:0xf
	v_fmac_f32_dpp v236, v124, v200 row_shr:1 row_mask:0xf bank_mask:0xf
	v_fmac_f32_dpp v237, v125, v201 row_shr:1 row_mask:0xf bank_mask:0xf
	v_fmac_f32_dpp v230, v126, v190 row_shl:1 row_mask:0xf bank_mask:0xf
	v_fmac_f32_dpp v231, v127, v191 row_shl:1 row_mask:0xf bank_mask:0xf
	v_fmac_f32_dpp v232, v128, v192 row_shl:1 row_mask:0xf bank_mask:0xf
	v_fmac_f32_dpp v233, v129, v193 row_shl:1 row_mask:0xf bank_mask:0xf
	v_fmac_f32_dpp v234, v122, v206 row_shl:1 row_mask:0xf bank_mask:0xf
	v_fmac_f32_dpp v235, v123, v207 row_shl:1 row_mask:0xf bank_mask:0xf
	v_fmac_f32_dpp v236, v124, v208 row_shl:1 row_mask:0xf bank_mask:0xf
	v_fmac_f32_dpp v237, v125, v209 row_shl:1 row_mask:0xf bank_mask:0xf
	v_fmac_f32_dpp v230, v118, v222 row_ror:15 row_mask:0xf bank_mask:0xf
	v_fmac_f32_dpp v231, v119, v223 row_ror:15 row_mask:0xf bank_mask:0xf
	v_fmac_f32_dpp v232, v120, v224 row_ror:15 row_mask:0xf bank_mask:0xf
	v_fmac_f32_dpp v233, v121, v225 row_ror:15 row_mask:0xf bank_mask:0xf
	v_fmac_f32_dpp v234, v114, v226 row_ror:15 row_mask:0xf bank_mask:0xf
	v_fmac_f32_dpp v235, v115, v227 row_ror:15 row_mask:0xf bank_mask:0xf
	v_fmac_f32_dpp v236, v116, v228 row_ror:15 row_mask:0xf bank_mask:0xf
	v_fmac_f32_dpp v237, v117, v229 row_ror:15 row_mask:0xf bank_mask:0xf
	v_pk_mul_f32 v[174:175], v[230:231], s[34:35]
	v_pk_mul_f32 v[176:177], v[232:233], s[34:35]
	v_exp_f32_e32 v174, v174
	v_exp_f32_e32 v175, v175
	v_exp_f32_e32 v176, v176
	v_exp_f32_e32 v177, v177
	v_pk_add_f32 v[174:175], v[174:175], s[36:37]
	v_pk_add_f32 v[176:177], v[176:177], s[36:37]
	v_rcp_f32_e32 v174, v174
	v_rcp_f32_e32 v175, v175
	v_rcp_f32_e32 v176, v176
	v_rcp_f32_e32 v177, v177
	v_pk_mul_f32 v[174:175], v[230:231], v[174:175]
	v_pk_mul_f32 v[176:177], v[232:233], v[176:177]
	v_pk_mul_f32 v[174:175], v[174:175], v[234:235]
	v_pk_mul_f32 v[176:177], v[176:177], v[236:237]
	v_cvt_pk_bf16_f32 v130, v174, v175
	v_cvt_pk_bf16_f32 v131, v176, v177
	v_pk_fma_f32 v[230:231], v[118:119], v[186:187], v[194:195]
	v_pk_fma_f32 v[232:233], v[120:121], v[188:189], v[196:197]
	v_pk_fma_f32 v[234:235], v[114:115], v[202:203], v[210:211]
	v_pk_fma_f32 v[236:237], v[116:117], v[204:205], v[212:213]
	v_fmac_f32_dpp v230, v118, v182 row_shr:1 row_mask:0xf bank_mask:0xf
	v_fmac_f32_dpp v231, v119, v183 row_shr:1 row_mask:0xf bank_mask:0xf
	v_fmac_f32_dpp v232, v120, v184 row_shr:1 row_mask:0xf bank_mask:0xf
	v_fmac_f32_dpp v233, v121, v185 row_shr:1 row_mask:0xf bank_mask:0xf
	v_fmac_f32_dpp v234, v114, v198 row_shr:1 row_mask:0xf bank_mask:0xf
	v_fmac_f32_dpp v235, v115, v199 row_shr:1 row_mask:0xf bank_mask:0xf
	v_fmac_f32_dpp v236, v116, v200 row_shr:1 row_mask:0xf bank_mask:0xf
	v_fmac_f32_dpp v237, v117, v201 row_shr:1 row_mask:0xf bank_mask:0xf
	v_fmac_f32_dpp v230, v118, v190 row_shl:1 row_mask:0xf bank_mask:0xf
	v_fmac_f32_dpp v231, v119, v191 row_shl:1 row_mask:0xf bank_mask:0xf
	v_fmac_f32_dpp v232, v120, v192 row_shl:1 row_mask:0xf bank_mask:0xf
	v_fmac_f32_dpp v233, v121, v193 row_shl:1 row_mask:0xf bank_mask:0xf
	v_fmac_f32_dpp v234, v114, v206 row_shl:1 row_mask:0xf bank_mask:0xf
	v_fmac_f32_dpp v235, v115, v207 row_shl:1 row_mask:0xf bank_mask:0xf
	v_fmac_f32_dpp v236, v116, v208 row_shl:1 row_mask:0xf bank_mask:0xf
	v_fmac_f32_dpp v237, v117, v209 row_shl:1 row_mask:0xf bank_mask:0xf
	v_fmac_f32_dpp v230, v126, v214 row_ror:1 row_mask:0xf bank_mask:0xf
	v_fmac_f32_dpp v231, v127, v215 row_ror:1 row_mask:0xf bank_mask:0xf
	v_fmac_f32_dpp v232, v128, v216 row_ror:1 row_mask:0xf bank_mask:0xf
	v_fmac_f32_dpp v233, v129, v217 row_ror:1 row_mask:0xf bank_mask:0xf
	v_fmac_f32_dpp v234, v122, v218 row_ror:1 row_mask:0xf bank_mask:0xf
	v_fmac_f32_dpp v235, v123, v219 row_ror:1 row_mask:0xf bank_mask:0xf
	v_fmac_f32_dpp v236, v124, v220 row_ror:1 row_mask:0xf bank_mask:0xf
	v_fmac_f32_dpp v237, v125, v221 row_ror:1 row_mask:0xf bank_mask:0xf
	v_fmac_f32_dpp v230, v110, v222 row_ror:15 row_mask:0xf bank_mask:0xf
	v_fmac_f32_dpp v231, v111, v223 row_ror:15 row_mask:0xf bank_mask:0xf
	v_fmac_f32_dpp v232, v112, v224 row_ror:15 row_mask:0xf bank_mask:0xf
	v_fmac_f32_dpp v233, v113, v225 row_ror:15 row_mask:0xf bank_mask:0xf
	v_fmac_f32_dpp v234, v102, v226 row_ror:15 row_mask:0xf bank_mask:0xf
	v_fmac_f32_dpp v235, v103, v227 row_ror:15 row_mask:0xf bank_mask:0xf
; __device__ __forceinline__ unsigned cvt_pk_bf16(float lo, float hi) { unsigned r; asm volatile("v_cvt_pk_bf16_f32 %0, %1, %2" : "=v"(r) : "v"(lo), "v"(hi)); return r; }
; __device__ __forceinline__ float sigmoid_f(float x) { return fast_rcp(1.0f + fast_exp2(-1.4426950409f * x)); }
;     __device__ __forceinline__ void operator()(f32x4 (&acc)[2][2][4][2], const Unit& u, int wr, int wc, int fr, int fq) const {
;     ...
;                 for (int m = 0; m < 4; ++m) {
;                     f32x4 cv[2];
; #pragma unroll
;                     for (int bj = 0; bj < 2; ++bj) {
;                         const f32x4 cur = acc[ai][bj][m][n], lo = acc[ai][bj][m > 0 ? m - 1 : 0][n], hi = acc[ai][bj][m < 3 ? m + 1 : 3][n];
;                         f32x4 pv, nv;
; #pragma unroll
;                         for (int idx = 0; idx < 4; ++idx) {
;                             const float y = (fr == 15) ? lo[idx] : cur[idx], z = (fr == 0) ? hi[idx] : cur[idx];
;                             pv[idx] = __int_as_float(__builtin_amdgcn_update_dpp(0, __float_as_int(y), 0x121, 0xf, 0xf, false));
;                             nv[idx] = __int_as_float(__builtin_amdgcn_update_dpp(0, __float_as_int(z), 0x12f, 0xf, 0xf, false));
;                         }
;                         cv[bj] = kc[bj][0] * pv + kc[bj][1] * cur + kc[bj][2] * nv + bc[bj];
;                     }
;                     const int row = row0 + ai * HALF + m * 16;
;                     const bool edge = (m == 0 && fr == 0) || (m == 3 && fr == 15);
;                     if (!edge) { const f32x4 gt = cv[0], vl = cv[1];
;                         u32x2 w; w.x = cvt_pk_bf16(gt[0] * sigmoid_f(gt[0]) * vl[0], gt[1] * sigmoid_f(gt[1]) * vl[1]); w.y = cvt_pk_bf16(gt[2] * sigmoid_f(gt[2]) * vl[2], gt[3] * sigmoid_f(gt[3]) * vl[3]);
;                         *(u32x2*)(ACT + (size_t)row * FF + j4) = w; }
	v_fmac_f32_dpp v236, v104, v228 row_ror:15 row_mask:0xf bank_mask:0xf
	v_fmac_f32_dpp v237, v105, v229 row_ror:15 row_mask:0xf bank_mask:0xf
	v_pk_mul_f32 v[174:175], v[230:231], s[34:35]
	v_pk_mul_f32 v[176:177], v[232:233], s[34:35]
	v_exp_f32_e32 v174, v174
	v_exp_f32_e32 v175, v175
	v_exp_f32_e32 v176, v176
	v_exp_f32_e32 v177, v177
	v_pk_add_f32 v[174:175], v[174:175], s[36:37]
	v_pk_add_f32 v[176:177], v[176:177], s[36:37]
	v_rcp_f32_e32 v174, v174
	v_rcp_f32_e32 v175, v175
	v_rcp_f32_e32 v176, v176
	v_rcp_f32_e32 v177, v177
	v_pk_mul_f32 v[174:175], v[230:231], v[174:175]
	v_pk_mul_f32 v[176:177], v[232:233], v[176:177]
	v_pk_mul_f32 v[174:175], v[174:175], v[234:235]
	v_pk_mul_f32 v[176:177], v[176:177], v[236:237]
	v_cvt_pk_bf16_f32 v134, v174, v175
	v_cvt_pk_bf16_f32 v135, v176, v177
	v_pk_fma_f32 v[230:231], v[110:111], v[186:187], v[194:195]
	v_pk_fma_f32 v[232:233], v[112:113], v[188:189], v[196:197]
	v_pk_fma_f32 v[234:235], v[102:103], v[202:203], v[210:211]
	v_pk_fma_f32 v[236:237], v[104:105], v[204:205], v[212:213]
	v_fmac_f32_dpp v230, v110, v182 row_shr:1 row_mask:0xf bank_mask:0xf
	v_fmac_f32_dpp v231, v111, v183 row_shr:1 row_mask:0xf bank_mask:0xf
	v_fmac_f32_dpp v232, v112, v184 row_shr:1 row_mask:0xf bank_mask:0xf
	v_fmac_f32_dpp v233, v113, v185 row_shr:1 row_mask:0xf bank_mask:0xf
	v_fmac_f32_dpp v234, v102, v198 row_shr:1 row_mask:0xf bank_mask:0xf
	v_fmac_f32_dpp v235, v103, v199 row_shr:1 row_mask:0xf bank_mask:0xf
	v_fmac_f32_dpp v236, v104, v200 row_shr:1 row_mask:0xf bank_mask:0xf
	v_fmac_f32_dpp v237, v105, v201 row_shr:1 row_mask:0xf bank_mask:0xf
	v_fmac_f32_dpp v230, v110, v190 row_shl:1 row_mask:0xf bank_mask:0xf
	v_fmac_f32_dpp v231, v111, v191 row_shl:1 row_mask:0xf bank_mask:0xf
	v_fmac_f32_dpp v232, v112, v192 row_shl:1 row_mask:0xf bank_mask:0xf
	v_fmac_f32_dpp v233, v113, v193 row_shl:1 row_mask:0xf bank_mask:0xf
	v_fmac_f32_dpp v234, v102, v206 row_shl:1 row_mask:0xf bank_mask:0xf
	v_fmac_f32_dpp v235, v103, v207 row_shl:1 row_mask:0xf bank_mask:0xf
	v_fmac_f32_dpp v236, v104, v208 row_shl:1 row_mask:0xf bank_mask:0xf
	v_fmac_f32_dpp v237, v105, v209 row_shl:1 row_mask:0xf bank_mask:0xf
	v_fmac_f32_dpp v230, v118, v214 row_ror:1 row_mask:0xf bank_mask:0xf
	v_fmac_f32_dpp v231, v119, v215 row_ror:1 row_mask:0xf bank_mask:0xf
	v_fmac_f32_dpp v232, v120, v216 row_ror:1 row_mask:0xf bank_mask:0xf
	v_fmac_f32_dpp v233, v121, v217 row_ror:1 row_mask:0xf bank_mask:0xf
	v_fmac_f32_dpp v234, v114, v218 row_ror:1 row_mask:0xf bank_mask:0xf
	v_fmac_f32_dpp v235, v115, v219 row_ror:1 row_mask:0xf bank_mask:0xf
	v_fmac_f32_dpp v236, v116, v220 row_ror:1 row_mask:0xf bank_mask:0xf
	v_fmac_f32_dpp v237, v117, v221 row_ror:1 row_mask:0xf bank_mask:0xf
	v_fmac_f32_dpp v230, v106, v222 row_ror:15 row_mask:0xf bank_mask:0xf
	v_fmac_f32_dpp v231, v107, v223 row_ror:15 row_mask:0xf bank_mask:0xf
	v_fmac_f32_dpp v232, v108, v224 row_ror:15 row_mask:0xf bank_mask:0xf
	v_fmac_f32_dpp v233, v109, v225 row_ror:15 row_mask:0xf bank_mask:0xf
	v_fmac_f32_dpp v234, v98, v226 row_ror:15 row_mask:0xf bank_mask:0xf
	v_fmac_f32_dpp v235, v99, v227 row_ror:15 row_mask:0xf bank_mask:0xf
	v_fmac_f32_dpp v236, v100, v228 row_ror:15 row_mask:0xf bank_mask:0xf
	v_fmac_f32_dpp v237, v101, v229 row_ror:15 row_mask:0xf bank_mask:0xf
	v_pk_mul_f32 v[174:175], v[230:231], s[34:35]
	v_pk_mul_f32 v[176:177], v[232:233], s[34:35]
	v_exp_f32_e32 v174, v174
	v_exp_f32_e32 v175, v175
	v_exp_f32_e32 v176, v176
	v_exp_f32_e32 v177, v177
	v_pk_add_f32 v[174:175], v[174:175], s[36:37]
	v_pk_add_f32 v[176:177], v[176:177], s[36:37]
	v_rcp_f32_e32 v174, v174
	v_rcp_f32_e32 v175, v175
	v_rcp_f32_e32 v176, v176
	v_rcp_f32_e32 v177, v177
	v_pk_mul_f32 v[174:175], v[230:231], v[174:175]
	v_pk_mul_f32 v[176:177], v[232:233], v[176:177]
	v_pk_mul_f32 v[174:175], v[174:175], v[234:235]
	v_pk_mul_f32 v[176:177], v[176:177], v[236:237]
	v_cvt_pk_bf16_f32 v138, v174, v175
	v_cvt_pk_bf16_f32 v139, v176, v177
	v_pk_fma_f32 v[230:231], v[106:107], v[186:187], v[194:195]
	v_pk_fma_f32 v[232:233], v[108:109], v[188:189], v[196:197]
	v_pk_fma_f32 v[234:235], v[98:99], v[202:203], v[210:211]
	v_pk_fma_f32 v[236:237], v[100:101], v[204:205], v[212:213]
	v_fmac_f32_dpp v230, v106, v182 row_shr:1 row_mask:0xf bank_mask:0xf
	v_fmac_f32_dpp v231, v107, v183 row_shr:1 row_mask:0xf bank_mask:0xf
	v_fmac_f32_dpp v232, v108, v184 row_shr:1 row_mask:0xf bank_mask:0xf
	v_fmac_f32_dpp v233, v109, v185 row_shr:1 row_mask:0xf bank_mask:0xf
	v_fmac_f32_dpp v234, v98, v198 row_shr:1 row_mask:0xf bank_mask:0xf
	v_fmac_f32_dpp v235, v99, v199 row_shr:1 row_mask:0xf bank_mask:0xf
	v_fmac_f32_dpp v236, v100, v200 row_shr:1 row_mask:0xf bank_mask:0xf
	v_fmac_f32_dpp v237, v101, v201 row_shr:1 row_mask:0xf bank_mask:0xf
	v_fmac_f32_dpp v230, v106, v190 row_shl:1 row_mask:0xf bank_mask:0xf
	v_fmac_f32_dpp v231, v107, v191 row_shl:1 row_mask:0xf bank_mask:0xf
	v_fmac_f32_dpp v232, v108, v192 row_shl:1 row_mask:0xf bank_mask:0xf
	v_fmac_f32_dpp v233, v109, v193 row_shl:1 row_mask:0xf bank_mask:0xf
	v_fmac_f32_dpp v234, v98, v206 row_shl:1 row_mask:0xf bank_mask:0xf
	v_fmac_f32_dpp v235, v99, v207 row_shl:1 row_mask:0xf bank_mask:0xf
	v_fmac_f32_dpp v236, v100, v208 row_shl:1 row_mask:0xf bank_mask:0xf
	v_fmac_f32_dpp v237, v101, v209 row_shl:1 row_mask:0xf bank_mask:0xf
	v_fmac_f32_dpp v230, v110, v214 row_ror:1 row_mask:0xf bank_mask:0xf
	v_fmac_f32_dpp v231, v111, v215 row_ror:1 row_mask:0xf bank_mask:0xf
	v_fmac_f32_dpp v232, v112, v216 row_ror:1 row_mask:0xf bank_mask:0xf
	v_fmac_f32_dpp v233, v113, v217 row_ror:1 row_mask:0xf bank_mask:0xf
	v_fmac_f32_dpp v234, v102, v218 row_ror:1 row_mask:0xf bank_mask:0xf
; __device__ __forceinline__ unsigned cvt_pk_bf16(float lo, float hi) { unsigned r; asm volatile("v_cvt_pk_bf16_f32 %0, %1, %2" : "=v"(r) : "v"(lo), "v"(hi)); return r; }
; __device__ __forceinline__ float sigmoid_f(float x) { return fast_rcp(1.0f + fast_exp2(-1.4426950409f * x)); }
;     __device__ __forceinline__ void operator()(f32x4 (&acc)[2][2][4][2], const Unit& u, int wr, int wc, int fr, int fq) const {
;     ...
;             for (int bj = 0; bj < 2; ++bj) { bc[bj] = *(const f32x4*)(cb + bj * FF + j4);
; #pragma unroll
;                 for (int w = 0; w < 3; ++w) kc[bj][w] = *(const f32x4*)(ck + w * NUP + bj * FF + j4); }
;     ...
;                 for (int m = 0; m < 4; ++m) {
;                     f32x4 cv[2];
; #pragma unroll
;                     for (int bj = 0; bj < 2; ++bj) {
;                         const f32x4 cur = acc[ai][bj][m][n], lo = acc[ai][bj][m > 0 ? m - 1 : 0][n], hi = acc[ai][bj][m < 3 ? m + 1 : 3][n];
;                         f32x4 pv, nv;
; #pragma unroll
;                         for (int idx = 0; idx < 4; ++idx) {
;                             const float y = (fr == 15) ? lo[idx] : cur[idx], z = (fr == 0) ? hi[idx] : cur[idx];
;                             pv[idx] = __int_as_float(__builtin_amdgcn_update_dpp(0, __float_as_int(y), 0x121, 0xf, 0xf, false));
;                             nv[idx] = __int_as_float(__builtin_amdgcn_update_dpp(0, __float_as_int(z), 0x12f, 0xf, 0xf, false));
;                         }
;                         cv[bj] = kc[bj][0] * pv + kc[bj][1] * cur + kc[bj][2] * nv + bc[bj];
;                     }
;                     const int row = row0 + ai * HALF + m * 16;
;                     const bool edge = (m == 0 && fr == 0) || (m == 3 && fr == 15);
;                     if (!edge) { const f32x4 gt = cv[0], vl = cv[1];
;                         u32x2 w; w.x = cvt_pk_bf16(gt[0] * sigmoid_f(gt[0]) * vl[0], gt[1] * sigmoid_f(gt[1]) * vl[1]); w.y = cvt_pk_bf16(gt[2] * sigmoid_f(gt[2]) * vl[2], gt[3] * sigmoid_f(gt[3]) * vl[3]);
;                         *(u32x2*)(ACT + (size_t)row * FF + j4) = w; }
	v_fmac_f32_dpp v235, v103, v219 row_ror:1 row_mask:0xf bank_mask:0xf
	v_fmac_f32_dpp v236, v104, v220 row_ror:1 row_mask:0xf bank_mask:0xf
	v_fmac_f32_dpp v237, v105, v221 row_ror:1 row_mask:0xf bank_mask:0xf
	v_pk_mul_f32 v[174:175], v[230:231], s[34:35]
	v_pk_mul_f32 v[176:177], v[232:233], s[34:35]
	v_exp_f32_e32 v174, v174
	v_exp_f32_e32 v175, v175
	v_exp_f32_e32 v176, v176
	v_exp_f32_e32 v177, v177
	v_pk_add_f32 v[174:175], v[174:175], s[36:37]
	v_pk_add_f32 v[176:177], v[176:177], s[36:37]
	v_rcp_f32_e32 v174, v174
	v_rcp_f32_e32 v175, v175
	v_rcp_f32_e32 v176, v176
	v_rcp_f32_e32 v177, v177
	v_pk_mul_f32 v[174:175], v[230:231], v[174:175]
	v_pk_mul_f32 v[176:177], v[232:233], v[176:177]
	v_pk_mul_f32 v[174:175], v[174:175], v[234:235]
	v_pk_mul_f32 v[176:177], v[176:177], v[236:237]
	v_cvt_pk_bf16_f32 v142, v174, v175
	v_cvt_pk_bf16_f32 v143, v176, v177
	v_add_u32_e32 v174, 0x5600, v242
	v_add_u32_e32 v175, 0xac00, v242
	v_add_u32_e32 v176, 0x10200, v242
	v_add_u32_e32 v177, 0x15800, v242
	v_add_u32_e32 v239, 0x1ae00, v242
	global_load_dwordx4 v[126:129], v242, s[18:19] offset:16
	global_load_dwordx4 v[118:121], v175, s[18:19] offset:16
	global_load_dwordx4 v[110:113], v177, s[18:19] offset:16
	global_load_dwordx4 v[106:109], v242, s[20:21] offset:16
	global_load_dwordx4 v[122:125], v174, s[18:19] offset:16
	global_load_dwordx4 v[114:117], v176, s[18:19] offset:16
	global_load_dwordx4 v[102:105], v239, s[18:19] offset:16
	global_load_dwordx4 v[98:101], v174, s[20:21] offset:16
	v_pk_fma_f32 v[230:231], v[94:95], v[186:187], v[194:195]
	v_pk_fma_f32 v[232:233], v[96:97], v[188:189], v[196:197]
	v_pk_fma_f32 v[234:235], v[86:87], v[202:203], v[210:211]
	v_pk_fma_f32 v[236:237], v[88:89], v[204:205], v[212:213]
	v_fmac_f32_dpp v230, v94, v182 row_shr:1 row_mask:0xf bank_mask:0xf
	v_fmac_f32_dpp v231, v95, v183 row_shr:1 row_mask:0xf bank_mask:0xf
	v_fmac_f32_dpp v232, v96, v184 row_shr:1 row_mask:0xf bank_mask:0xf
	v_fmac_f32_dpp v233, v97, v185 row_shr:1 row_mask:0xf bank_mask:0xf
	v_fmac_f32_dpp v234, v86, v198 row_shr:1 row_mask:0xf bank_mask:0xf
	v_fmac_f32_dpp v235, v87, v199 row_shr:1 row_mask:0xf bank_mask:0xf
	v_fmac_f32_dpp v236, v88, v200 row_shr:1 row_mask:0xf bank_mask:0xf
	v_fmac_f32_dpp v237, v89, v201 row_shr:1 row_mask:0xf bank_mask:0xf
	v_fmac_f32_dpp v230, v94, v190 row_shl:1 row_mask:0xf bank_mask:0xf
	v_fmac_f32_dpp v231, v95, v191 row_shl:1 row_mask:0xf bank_mask:0xf
	v_fmac_f32_dpp v232, v96, v192 row_shl:1 row_mask:0xf bank_mask:0xf
	v_fmac_f32_dpp v233, v97, v193 row_shl:1 row_mask:0xf bank_mask:0xf
	v_fmac_f32_dpp v234, v86, v206 row_shl:1 row_mask:0xf bank_mask:0xf
	v_fmac_f32_dpp v235, v87, v207 row_shl:1 row_mask:0xf bank_mask:0xf
	v_fmac_f32_dpp v236, v88, v208 row_shl:1 row_mask:0xf bank_mask:0xf
	v_fmac_f32_dpp v237, v89, v209 row_shl:1 row_mask:0xf bank_mask:0xf
	v_fmac_f32_dpp v230, v90, v222 row_ror:15 row_mask:0xf bank_mask:0xf
	v_fmac_f32_dpp v231, v91, v223 row_ror:15 row_mask:0xf bank_mask:0xf
	v_fmac_f32_dpp v232, v92, v224 row_ror:15 row_mask:0xf bank_mask:0xf
	v_fmac_f32_dpp v233, v93, v225 row_ror:15 row_mask:0xf bank_mask:0xf
	v_fmac_f32_dpp v234, v82, v226 row_ror:15 row_mask:0xf bank_mask:0xf
	v_fmac_f32_dpp v235, v83, v227 row_ror:15 row_mask:0xf bank_mask:0xf
	v_fmac_f32_dpp v236, v84, v228 row_ror:15 row_mask:0xf bank_mask:0xf
	v_fmac_f32_dpp v237, v85, v229 row_ror:15 row_mask:0xf bank_mask:0xf
	v_pk_mul_f32 v[174:175], v[230:231], s[34:35]
	v_pk_mul_f32 v[176:177], v[232:233], s[34:35]
	v_exp_f32_e32 v174, v174
	v_exp_f32_e32 v175, v175
	v_exp_f32_e32 v176, v176
	v_exp_f32_e32 v177, v177
	v_pk_add_f32 v[174:175], v[174:175], s[36:37]
	v_pk_add_f32 v[176:177], v[176:177], s[36:37]
	v_rcp_f32_e32 v174, v174
	v_rcp_f32_e32 v175, v175
	v_rcp_f32_e32 v176, v176
	v_rcp_f32_e32 v177, v177
	v_pk_mul_f32 v[174:175], v[230:231], v[174:175]
	v_pk_mul_f32 v[176:177], v[232:233], v[176:177]
	v_pk_mul_f32 v[174:175], v[174:175], v[234:235]
	v_pk_mul_f32 v[176:177], v[176:177], v[236:237]
	v_cvt_pk_bf16_f32 v178, v174, v175
	v_cvt_pk_bf16_f32 v179, v176, v177
	v_pk_fma_f32 v[230:231], v[90:91], v[186:187], v[194:195]
	v_pk_fma_f32 v[232:233], v[92:93], v[188:189], v[196:197]
	v_pk_fma_f32 v[234:235], v[82:83], v[202:203], v[210:211]
	v_pk_fma_f32 v[236:237], v[84:85], v[204:205], v[212:213]
	v_fmac_f32_dpp v230, v90, v182 row_shr:1 row_mask:0xf bank_mask:0xf
	v_fmac_f32_dpp v231, v91, v183 row_shr:1 row_mask:0xf bank_mask:0xf
	v_fmac_f32_dpp v232, v92, v184 row_shr:1 row_mask:0xf bank_mask:0xf
	v_fmac_f32_dpp v233, v93, v185 row_shr:1 row_mask:0xf bank_mask:0xf
	v_fmac_f32_dpp v234, v82, v198 row_shr:1 row_mask:0xf bank_mask:0xf
	v_fmac_f32_dpp v235, v83, v199 row_shr:1 row_mask:0xf bank_mask:0xf
	v_fmac_f32_dpp v236, v84, v200 row_shr:1 row_mask:0xf bank_mask:0xf
	v_fmac_f32_dpp v237, v85, v201 row_shr:1 row_mask:0xf bank_mask:0xf
	v_fmac_f32_dpp v230, v90, v190 row_shl:1 row_mask:0xf bank_mask:0xf
	v_fmac_f32_dpp v231, v91, v191 row_shl:1 row_mask:0xf bank_mask:0xf
	v_fmac_f32_dpp v232, v92, v192 row_shl:1 row_mask:0xf bank_mask:0xf
	v_fmac_f32_dpp v233, v93, v193 row_shl:1 row_mask:0xf bank_mask:0xf
	v_fmac_f32_dpp v234, v82, v206 row_shl:1 row_mask:0xf bank_mask:0xf
	v_fmac_f32_dpp v235, v83, v207 row_shl:1 row_mask:0xf bank_mask:0xf
	v_fmac_f32_dpp v236, v84, v208 row_shl:1 row_mask:0xf bank_mask:0xf
	v_fmac_f32_dpp v237, v85, v209 row_shl:1 row_mask:0xf bank_mask:0xf
	v_fmac_f32_dpp v230, v94, v214 row_ror:1 row_mask:0xf bank_mask:0xf
	v_fmac_f32_dpp v231, v95, v215 row_ror:1 row_mask:0xf bank_mask:0xf
	v_fmac_f32_dpp v232, v96, v216 row_ror:1 row_mask:0xf bank_mask:0xf
; __device__ __forceinline__ unsigned cvt_pk_bf16(float lo, float hi) { unsigned r; asm volatile("v_cvt_pk_bf16_f32 %0, %1, %2" : "=v"(r) : "v"(lo), "v"(hi)); return r; }
; __device__ __forceinline__ float sigmoid_f(float x) { return fast_rcp(1.0f + fast_exp2(-1.4426950409f * x)); }
;     __device__ __forceinline__ void operator()(f32x4 (&acc)[2][2][4][2], const Unit& u, int wr, int wc, int fr, int fq) const {
;     ...
;                 for (int m = 0; m < 4; ++m) {
;                     f32x4 cv[2];
; #pragma unroll
;                     for (int bj = 0; bj < 2; ++bj) {
;                         const f32x4 cur = acc[ai][bj][m][n], lo = acc[ai][bj][m > 0 ? m - 1 : 0][n], hi = acc[ai][bj][m < 3 ? m + 1 : 3][n];
;                         f32x4 pv, nv;
; #pragma unroll
;                         for (int idx = 0; idx < 4; ++idx) {
;                             const float y = (fr == 15) ? lo[idx] : cur[idx], z = (fr == 0) ? hi[idx] : cur[idx];
;                             pv[idx] = __int_as_float(__builtin_amdgcn_update_dpp(0, __float_as_int(y), 0x121, 0xf, 0xf, false));
;                             nv[idx] = __int_as_float(__builtin_amdgcn_update_dpp(0, __float_as_int(z), 0x12f, 0xf, 0xf, false));
;                         }
;                         cv[bj] = kc[bj][0] * pv + kc[bj][1] * cur + kc[bj][2] * nv + bc[bj];
;                     }
;                     const int row = row0 + ai * HALF + m * 16;
;                     const bool edge = (m == 0 && fr == 0) || (m == 3 && fr == 15);
;                     if (!edge) { const f32x4 gt = cv[0], vl = cv[1];
;                         u32x2 w; w.x = cvt_pk_bf16(gt[0] * sigmoid_f(gt[0]) * vl[0], gt[1] * sigmoid_f(gt[1]) * vl[1]); w.y = cvt_pk_bf16(gt[2] * sigmoid_f(gt[2]) * vl[2], gt[3] * sigmoid_f(gt[3]) * vl[3]);
;                         *(u32x2*)(ACT + (size_t)row * FF + j4) = w; }
	v_fmac_f32_dpp v233, v97, v217 row_ror:1 row_mask:0xf bank_mask:0xf
	v_fmac_f32_dpp v234, v86, v218 row_ror:1 row_mask:0xf bank_mask:0xf
	v_fmac_f32_dpp v235, v87, v219 row_ror:1 row_mask:0xf bank_mask:0xf
	v_fmac_f32_dpp v236, v88, v220 row_ror:1 row_mask:0xf bank_mask:0xf
	v_fmac_f32_dpp v237, v89, v221 row_ror:1 row_mask:0xf bank_mask:0xf
	v_fmac_f32_dpp v230, v78, v222 row_ror:15 row_mask:0xf bank_mask:0xf
	v_fmac_f32_dpp v231, v79, v223 row_ror:15 row_mask:0xf bank_mask:0xf
	v_fmac_f32_dpp v232, v80, v224 row_ror:15 row_mask:0xf bank_mask:0xf
	v_fmac_f32_dpp v233, v81, v225 row_ror:15 row_mask:0xf bank_mask:0xf
	v_fmac_f32_dpp v234, v70, v226 row_ror:15 row_mask:0xf bank_mask:0xf
	v_fmac_f32_dpp v235, v71, v227 row_ror:15 row_mask:0xf bank_mask:0xf
	v_fmac_f32_dpp v236, v72, v228 row_ror:15 row_mask:0xf bank_mask:0xf
	v_fmac_f32_dpp v237, v73, v229 row_ror:15 row_mask:0xf bank_mask:0xf
	v_pk_mul_f32 v[174:175], v[230:231], s[34:35]
	v_pk_mul_f32 v[176:177], v[232:233], s[34:35]
	v_exp_f32_e32 v174, v174
	v_exp_f32_e32 v175, v175
	v_exp_f32_e32 v176, v176
	v_exp_f32_e32 v177, v177
	v_pk_add_f32 v[174:175], v[174:175], s[36:37]
	v_pk_add_f32 v[176:177], v[176:177], s[36:37]
	v_rcp_f32_e32 v174, v174
	v_rcp_f32_e32 v175, v175
	v_rcp_f32_e32 v176, v176
	v_rcp_f32_e32 v177, v177
	v_pk_mul_f32 v[174:175], v[230:231], v[174:175]
	v_pk_mul_f32 v[176:177], v[232:233], v[176:177]
	v_pk_mul_f32 v[174:175], v[174:175], v[234:235]
	v_pk_mul_f32 v[176:177], v[176:177], v[236:237]
	v_cvt_pk_bf16_f32 v94, v174, v175
	v_cvt_pk_bf16_f32 v95, v176, v177
	v_pk_fma_f32 v[230:231], v[78:79], v[186:187], v[194:195]
	v_pk_fma_f32 v[232:233], v[80:81], v[188:189], v[196:197]
	v_pk_fma_f32 v[234:235], v[70:71], v[202:203], v[210:211]
	v_pk_fma_f32 v[236:237], v[72:73], v[204:205], v[212:213]
	v_fmac_f32_dpp v230, v78, v182 row_shr:1 row_mask:0xf bank_mask:0xf
	v_fmac_f32_dpp v231, v79, v183 row_shr:1 row_mask:0xf bank_mask:0xf
	v_fmac_f32_dpp v232, v80, v184 row_shr:1 row_mask:0xf bank_mask:0xf
	v_fmac_f32_dpp v233, v81, v185 row_shr:1 row_mask:0xf bank_mask:0xf
	v_fmac_f32_dpp v234, v70, v198 row_shr:1 row_mask:0xf bank_mask:0xf
	v_fmac_f32_dpp v235, v71, v199 row_shr:1 row_mask:0xf bank_mask:0xf
	v_fmac_f32_dpp v236, v72, v200 row_shr:1 row_mask:0xf bank_mask:0xf
	v_fmac_f32_dpp v237, v73, v201 row_shr:1 row_mask:0xf bank_mask:0xf
	v_fmac_f32_dpp v230, v78, v190 row_shl:1 row_mask:0xf bank_mask:0xf
	v_fmac_f32_dpp v231, v79, v191 row_shl:1 row_mask:0xf bank_mask:0xf
	v_fmac_f32_dpp v232, v80, v192 row_shl:1 row_mask:0xf bank_mask:0xf
	v_fmac_f32_dpp v233, v81, v193 row_shl:1 row_mask:0xf bank_mask:0xf
	v_fmac_f32_dpp v234, v70, v206 row_shl:1 row_mask:0xf bank_mask:0xf
	v_fmac_f32_dpp v235, v71, v207 row_shl:1 row_mask:0xf bank_mask:0xf
	v_fmac_f32_dpp v236, v72, v208 row_shl:1 row_mask:0xf bank_mask:0xf
	v_fmac_f32_dpp v237, v73, v209 row_shl:1 row_mask:0xf bank_mask:0xf
	v_fmac_f32_dpp v230, v90, v214 row_ror:1 row_mask:0xf bank_mask:0xf
	v_fmac_f32_dpp v231, v91, v215 row_ror:1 row_mask:0xf bank_mask:0xf
	v_fmac_f32_dpp v232, v92, v216 row_ror:1 row_mask:0xf bank_mask:0xf
	v_fmac_f32_dpp v233, v93, v217 row_ror:1 row_mask:0xf bank_mask:0xf
	v_fmac_f32_dpp v234, v82, v218 row_ror:1 row_mask:0xf bank_mask:0xf
	v_fmac_f32_dpp v235, v83, v219 row_ror:1 row_mask:0xf bank_mask:0xf
	v_fmac_f32_dpp v236, v84, v220 row_ror:1 row_mask:0xf bank_mask:0xf
	v_fmac_f32_dpp v237, v85, v221 row_ror:1 row_mask:0xf bank_mask:0xf
	v_fmac_f32_dpp v230, v74, v222 row_ror:15 row_mask:0xf bank_mask:0xf
	v_fmac_f32_dpp v231, v75, v223 row_ror:15 row_mask:0xf bank_mask:0xf
	v_fmac_f32_dpp v232, v76, v224 row_ror:15 row_mask:0xf bank_mask:0xf
	v_fmac_f32_dpp v233, v77, v225 row_ror:15 row_mask:0xf bank_mask:0xf
	v_fmac_f32_dpp v234, v66, v226 row_ror:15 row_mask:0xf bank_mask:0xf
	v_fmac_f32_dpp v235, v67, v227 row_ror:15 row_mask:0xf bank_mask:0xf
	v_fmac_f32_dpp v236, v68, v228 row_ror:15 row_mask:0xf bank_mask:0xf
	v_fmac_f32_dpp v237, v69, v229 row_ror:15 row_mask:0xf bank_mask:0xf
	v_pk_mul_f32 v[174:175], v[230:231], s[34:35]
	v_pk_mul_f32 v[176:177], v[232:233], s[34:35]
	v_exp_f32_e32 v174, v174
	v_exp_f32_e32 v175, v175
	v_exp_f32_e32 v176, v176
	v_exp_f32_e32 v177, v177
	v_pk_add_f32 v[174:175], v[174:175], s[36:37]
	v_pk_add_f32 v[176:177], v[176:177], s[36:37]
	v_rcp_f32_e32 v174, v174
	v_rcp_f32_e32 v175, v175
	v_rcp_f32_e32 v176, v176
	v_rcp_f32_e32 v177, v177
	v_pk_mul_f32 v[174:175], v[230:231], v[174:175]
	v_pk_mul_f32 v[176:177], v[232:233], v[176:177]
	v_pk_mul_f32 v[174:175], v[174:175], v[234:235]
	v_pk_mul_f32 v[176:177], v[176:177], v[236:237]
	v_cvt_pk_bf16_f32 v90, v174, v175
	v_cvt_pk_bf16_f32 v91, v176, v177
	v_pk_fma_f32 v[230:231], v[74:75], v[186:187], v[194:195]
	v_pk_fma_f32 v[232:233], v[76:77], v[188:189], v[196:197]
	v_pk_fma_f32 v[234:235], v[66:67], v[202:203], v[210:211]
	v_pk_fma_f32 v[236:237], v[68:69], v[204:205], v[212:213]
	v_fmac_f32_dpp v230, v74, v182 row_shr:1 row_mask:0xf bank_mask:0xf
	v_fmac_f32_dpp v231, v75, v183 row_shr:1 row_mask:0xf bank_mask:0xf
	v_fmac_f32_dpp v232, v76, v184 row_shr:1 row_mask:0xf bank_mask:0xf
	v_fmac_f32_dpp v233, v77, v185 row_shr:1 row_mask:0xf bank_mask:0xf
	v_fmac_f32_dpp v234, v66, v198 row_shr:1 row_mask:0xf bank_mask:0xf
	v_fmac_f32_dpp v235, v67, v199 row_shr:1 row_mask:0xf bank_mask:0xf
	v_fmac_f32_dpp v236, v68, v200 row_shr:1 row_mask:0xf bank_mask:0xf
	v_fmac_f32_dpp v237, v69, v201 row_shr:1 row_mask:0xf bank_mask:0xf
	v_fmac_f32_dpp v230, v74, v190 row_shl:1 row_mask:0xf bank_mask:0xf
	v_fmac_f32_dpp v231, v75, v191 row_shl:1 row_mask:0xf bank_mask:0xf
; __device__ __forceinline__ unsigned cvt_pk_bf16(float lo, float hi) { unsigned r; asm volatile("v_cvt_pk_bf16_f32 %0, %1, %2" : "=v"(r) : "v"(lo), "v"(hi)); return r; }
; __device__ __forceinline__ float sigmoid_f(float x) { return fast_rcp(1.0f + fast_exp2(-1.4426950409f * x)); }
;     __device__ __forceinline__ void operator()(f32x4 (&acc)[2][2][4][2], const Unit& u, int wr, int wc, int fr, int fq) const {
;     ...
;                 for (int m = 0; m < 4; ++m) {
;                     f32x4 cv[2];
; #pragma unroll
;                     for (int bj = 0; bj < 2; ++bj) {
;                         const f32x4 cur = acc[ai][bj][m][n], lo = acc[ai][bj][m > 0 ? m - 1 : 0][n], hi = acc[ai][bj][m < 3 ? m + 1 : 3][n];
;                         f32x4 pv, nv;
; #pragma unroll
;                         for (int idx = 0; idx < 4; ++idx) {
;                             const float y = (fr == 15) ? lo[idx] : cur[idx], z = (fr == 0) ? hi[idx] : cur[idx];
;                             pv[idx] = __int_as_float(__builtin_amdgcn_update_dpp(0, __float_as_int(y), 0x121, 0xf, 0xf, false));
;                             nv[idx] = __int_as_float(__builtin_amdgcn_update_dpp(0, __float_as_int(z), 0x12f, 0xf, 0xf, false));
;                         }
;                         cv[bj] = kc[bj][0] * pv + kc[bj][1] * cur + kc[bj][2] * nv + bc[bj];
;                     }
;                     const int row = row0 + ai * HALF + m * 16;
;                     const bool edge = (m == 0 && fr == 0) || (m == 3 && fr == 15);
;                     if (!edge) { const f32x4 gt = cv[0], vl = cv[1];
;                         u32x2 w; w.x = cvt_pk_bf16(gt[0] * sigmoid_f(gt[0]) * vl[0], gt[1] * sigmoid_f(gt[1]) * vl[1]); w.y = cvt_pk_bf16(gt[2] * sigmoid_f(gt[2]) * vl[2], gt[3] * sigmoid_f(gt[3]) * vl[3]);
;                         *(u32x2*)(ACT + (size_t)row * FF + j4) = w; }
	v_fmac_f32_dpp v232, v76, v192 row_shl:1 row_mask:0xf bank_mask:0xf
	v_fmac_f32_dpp v233, v77, v193 row_shl:1 row_mask:0xf bank_mask:0xf
	v_fmac_f32_dpp v234, v66, v206 row_shl:1 row_mask:0xf bank_mask:0xf
	v_fmac_f32_dpp v235, v67, v207 row_shl:1 row_mask:0xf bank_mask:0xf
	v_fmac_f32_dpp v236, v68, v208 row_shl:1 row_mask:0xf bank_mask:0xf
	v_fmac_f32_dpp v237, v69, v209 row_shl:1 row_mask:0xf bank_mask:0xf
	v_fmac_f32_dpp v230, v78, v214 row_ror:1 row_mask:0xf bank_mask:0xf
	v_fmac_f32_dpp v231, v79, v215 row_ror:1 row_mask:0xf bank_mask:0xf
	v_fmac_f32_dpp v232, v80, v216 row_ror:1 row_mask:0xf bank_mask:0xf
	v_fmac_f32_dpp v233, v81, v217 row_ror:1 row_mask:0xf bank_mask:0xf
	v_fmac_f32_dpp v234, v70, v218 row_ror:1 row_mask:0xf bank_mask:0xf
	v_fmac_f32_dpp v235, v71, v219 row_ror:1 row_mask:0xf bank_mask:0xf
	v_fmac_f32_dpp v236, v72, v220 row_ror:1 row_mask:0xf bank_mask:0xf
	v_fmac_f32_dpp v237, v73, v221 row_ror:1 row_mask:0xf bank_mask:0xf
	v_pk_mul_f32 v[174:175], v[230:231], s[34:35]
	v_pk_mul_f32 v[176:177], v[232:233], s[34:35]
	v_exp_f32_e32 v174, v174
	v_exp_f32_e32 v175, v175
	v_exp_f32_e32 v176, v176
	v_exp_f32_e32 v177, v177
	v_pk_add_f32 v[174:175], v[174:175], s[36:37]
	v_pk_add_f32 v[176:177], v[176:177], s[36:37]
	v_rcp_f32_e32 v174, v174
	v_rcp_f32_e32 v175, v175
	v_rcp_f32_e32 v176, v176
	v_rcp_f32_e32 v177, v177
	v_pk_mul_f32 v[174:175], v[230:231], v[174:175]
	v_pk_mul_f32 v[176:177], v[232:233], v[176:177]
	v_pk_mul_f32 v[174:175], v[174:175], v[234:235]
	v_pk_mul_f32 v[176:177], v[176:177], v[236:237]
	v_cvt_pk_bf16_f32 v78, v174, v175
	v_cvt_pk_bf16_f32 v79, v176, v177
	s_waitcnt vmcnt(0)
	v_cndmask_b32_e64 v214, 0, v126, s[42:43]
	v_cndmask_b32_e64 v215, 0, v127, s[42:43]
	v_cndmask_b32_e64 v216, 0, v128, s[42:43]
	v_cndmask_b32_e64 v217, 0, v129, s[42:43]
	v_cndmask_b32_e64 v218, 0, v122, s[42:43]
	v_cndmask_b32_e64 v219, 0, v123, s[42:43]
	v_cndmask_b32_e64 v220, 0, v124, s[42:43]
	v_cndmask_b32_e64 v221, 0, v125, s[42:43]
	v_cndmask_b32_e64 v222, 0, v110, s[38:39]
	v_cndmask_b32_e64 v223, 0, v111, s[38:39]
	v_cndmask_b32_e64 v224, 0, v112, s[38:39]
	v_cndmask_b32_e64 v225, 0, v113, s[38:39]
	v_cndmask_b32_e64 v226, 0, v102, s[38:39]
	v_cndmask_b32_e64 v227, 0, v103, s[38:39]
	v_cndmask_b32_e64 v228, 0, v104, s[38:39]
	v_cndmask_b32_e64 v229, 0, v105, s[38:39]
	v_pk_fma_f32 v[230:231], v[62:63], v[118:119], v[106:107]
	v_pk_fma_f32 v[232:233], v[64:65], v[120:121], v[108:109]
	v_pk_fma_f32 v[234:235], v[54:55], v[114:115], v[98:99]
	v_pk_fma_f32 v[236:237], v[56:57], v[116:117], v[100:101]
	v_fmac_f32_dpp v230, v62, v126 row_shr:1 row_mask:0xf bank_mask:0xf
	v_fmac_f32_dpp v231, v63, v127 row_shr:1 row_mask:0xf bank_mask:0xf
	v_fmac_f32_dpp v232, v64, v128 row_shr:1 row_mask:0xf bank_mask:0xf
	v_fmac_f32_dpp v233, v65, v129 row_shr:1 row_mask:0xf bank_mask:0xf
	v_fmac_f32_dpp v234, v54, v122 row_shr:1 row_mask:0xf bank_mask:0xf
	v_fmac_f32_dpp v235, v55, v123 row_shr:1 row_mask:0xf bank_mask:0xf
	v_fmac_f32_dpp v236, v56, v124 row_shr:1 row_mask:0xf bank_mask:0xf
	v_fmac_f32_dpp v237, v57, v125 row_shr:1 row_mask:0xf bank_mask:0xf
	v_fmac_f32_dpp v230, v62, v110 row_shl:1 row_mask:0xf bank_mask:0xf
	v_fmac_f32_dpp v231, v63, v111 row_shl:1 row_mask:0xf bank_mask:0xf
	v_fmac_f32_dpp v232, v64, v112 row_shl:1 row_mask:0xf bank_mask:0xf
	v_fmac_f32_dpp v233, v65, v113 row_shl:1 row_mask:0xf bank_mask:0xf
	v_fmac_f32_dpp v234, v54, v102 row_shl:1 row_mask:0xf bank_mask:0xf
	v_fmac_f32_dpp v235, v55, v103 row_shl:1 row_mask:0xf bank_mask:0xf
	v_fmac_f32_dpp v236, v56, v104 row_shl:1 row_mask:0xf bank_mask:0xf
	v_fmac_f32_dpp v237, v57, v105 row_shl:1 row_mask:0xf bank_mask:0xf
	v_fmac_f32_dpp v230, v58, v222 row_ror:15 row_mask:0xf bank_mask:0xf
	v_fmac_f32_dpp v231, v59, v223 row_ror:15 row_mask:0xf bank_mask:0xf
	v_fmac_f32_dpp v232, v60, v224 row_ror:15 row_mask:0xf bank_mask:0xf
	v_fmac_f32_dpp v233, v61, v225 row_ror:15 row_mask:0xf bank_mask:0xf
	v_fmac_f32_dpp v234, v50, v226 row_ror:15 row_mask:0xf bank_mask:0xf
	v_fmac_f32_dpp v235, v51, v227 row_ror:15 row_mask:0xf bank_mask:0xf
	v_fmac_f32_dpp v236, v52, v228 row_ror:15 row_mask:0xf bank_mask:0xf
	v_fmac_f32_dpp v237, v53, v229 row_ror:15 row_mask:0xf bank_mask:0xf
	v_pk_mul_f32 v[174:175], v[230:231], s[34:35]
	v_pk_mul_f32 v[176:177], v[232:233], s[34:35]
	v_exp_f32_e32 v174, v174
	v_exp_f32_e32 v175, v175
	v_exp_f32_e32 v176, v176
	v_exp_f32_e32 v177, v177
	v_pk_add_f32 v[174:175], v[174:175], s[36:37]
	v_pk_add_f32 v[176:177], v[176:177], s[36:37]
	v_rcp_f32_e32 v174, v174
	v_rcp_f32_e32 v175, v175
	v_rcp_f32_e32 v176, v176
	v_rcp_f32_e32 v177, v177
	v_pk_mul_f32 v[174:175], v[230:231], v[174:175]
	v_pk_mul_f32 v[176:177], v[232:233], v[176:177]
	v_pk_mul_f32 v[174:175], v[174:175], v[234:235]
	v_pk_mul_f32 v[176:177], v[176:177], v[236:237]
	v_cvt_pk_bf16_f32 v132, v174, v175
	v_cvt_pk_bf16_f32 v133, v176, v177
	s_and_saveexec_b64 s[16:17], s[44:45]
	global_store_dwordx4 v238, v[130:133], s[30:31]
	s_or_b64 exec, exec, s[16:17]
	v_pk_fma_f32 v[230:231], v[58:59], v[118:119], v[106:107]
	v_pk_fma_f32 v[232:233], v[60:61], v[120:121], v[108:109]
	v_pk_fma_f32 v[234:235], v[50:51], v[114:115], v[98:99]
	v_pk_fma_f32 v[236:237], v[52:53], v[116:117], v[100:101]
	v_fmac_f32_dpp v230, v58, v126 row_shr:1 row_mask:0xf bank_mask:0xf
	v_fmac_f32_dpp v231, v59, v127 row_shr:1 row_mask:0xf bank_mask:0xf
	v_fmac_f32_dpp v232, v60, v128 row_shr:1 row_mask:0xf bank_mask:0xf
	v_fmac_f32_dpp v233, v61, v129 row_shr:1 row_mask:0xf bank_mask:0xf
	v_fmac_f32_dpp v234, v50, v122 row_shr:1 row_mask:0xf bank_mask:0xf
	v_fmac_f32_dpp v235, v51, v123 row_shr:1 row_mask:0xf bank_mask:0xf
; __device__ __forceinline__ unsigned cvt_pk_bf16(float lo, float hi) { unsigned r; asm volatile("v_cvt_pk_bf16_f32 %0, %1, %2" : "=v"(r) : "v"(lo), "v"(hi)); return r; }
; __device__ __forceinline__ float sigmoid_f(float x) { return fast_rcp(1.0f + fast_exp2(-1.4426950409f * x)); }
;     __device__ __forceinline__ void operator()(f32x4 (&acc)[2][2][4][2], const Unit& u, int wr, int wc, int fr, int fq) const {
;     ...
;                 for (int m = 0; m < 4; ++m) {
;                     f32x4 cv[2];
; #pragma unroll
;                     for (int bj = 0; bj < 2; ++bj) {
;                         const f32x4 cur = acc[ai][bj][m][n], lo = acc[ai][bj][m > 0 ? m - 1 : 0][n], hi = acc[ai][bj][m < 3 ? m + 1 : 3][n];
;                         f32x4 pv, nv;
; #pragma unroll
;                         for (int idx = 0; idx < 4; ++idx) {
;                             const float y = (fr == 15) ? lo[idx] : cur[idx], z = (fr == 0) ? hi[idx] : cur[idx];
;                             pv[idx] = __int_as_float(__builtin_amdgcn_update_dpp(0, __float_as_int(y), 0x121, 0xf, 0xf, false));
;                             nv[idx] = __int_as_float(__builtin_amdgcn_update_dpp(0, __float_as_int(z), 0x12f, 0xf, 0xf, false));
;                         }
;                         cv[bj] = kc[bj][0] * pv + kc[bj][1] * cur + kc[bj][2] * nv + bc[bj];
;                     }
;                     const int row = row0 + ai * HALF + m * 16;
;                     const bool edge = (m == 0 && fr == 0) || (m == 3 && fr == 15);
;                     if (!edge) { const f32x4 gt = cv[0], vl = cv[1];
;                         u32x2 w; w.x = cvt_pk_bf16(gt[0] * sigmoid_f(gt[0]) * vl[0], gt[1] * sigmoid_f(gt[1]) * vl[1]); w.y = cvt_pk_bf16(gt[2] * sigmoid_f(gt[2]) * vl[2], gt[3] * sigmoid_f(gt[3]) * vl[3]);
;                         *(u32x2*)(ACT + (size_t)row * FF + j4) = w; }
	v_fmac_f32_dpp v236, v52, v124 row_shr:1 row_mask:0xf bank_mask:0xf
	v_fmac_f32_dpp v237, v53, v125 row_shr:1 row_mask:0xf bank_mask:0xf
	v_fmac_f32_dpp v230, v58, v110 row_shl:1 row_mask:0xf bank_mask:0xf
	v_fmac_f32_dpp v231, v59, v111 row_shl:1 row_mask:0xf bank_mask:0xf
	v_fmac_f32_dpp v232, v60, v112 row_shl:1 row_mask:0xf bank_mask:0xf
	v_fmac_f32_dpp v233, v61, v113 row_shl:1 row_mask:0xf bank_mask:0xf
	v_fmac_f32_dpp v234, v50, v102 row_shl:1 row_mask:0xf bank_mask:0xf
	v_fmac_f32_dpp v235, v51, v103 row_shl:1 row_mask:0xf bank_mask:0xf
	v_fmac_f32_dpp v236, v52, v104 row_shl:1 row_mask:0xf bank_mask:0xf
	v_fmac_f32_dpp v237, v53, v105 row_shl:1 row_mask:0xf bank_mask:0xf
	v_fmac_f32_dpp v230, v62, v214 row_ror:1 row_mask:0xf bank_mask:0xf
	v_fmac_f32_dpp v231, v63, v215 row_ror:1 row_mask:0xf bank_mask:0xf
	v_fmac_f32_dpp v232, v64, v216 row_ror:1 row_mask:0xf bank_mask:0xf
	v_fmac_f32_dpp v233, v65, v217 row_ror:1 row_mask:0xf bank_mask:0xf
	v_fmac_f32_dpp v234, v54, v218 row_ror:1 row_mask:0xf bank_mask:0xf
	v_fmac_f32_dpp v235, v55, v219 row_ror:1 row_mask:0xf bank_mask:0xf
	v_fmac_f32_dpp v236, v56, v220 row_ror:1 row_mask:0xf bank_mask:0xf
	v_fmac_f32_dpp v237, v57, v221 row_ror:1 row_mask:0xf bank_mask:0xf
	v_fmac_f32_dpp v230, v46, v222 row_ror:15 row_mask:0xf bank_mask:0xf
	v_fmac_f32_dpp v231, v47, v223 row_ror:15 row_mask:0xf bank_mask:0xf
	v_fmac_f32_dpp v232, v48, v224 row_ror:15 row_mask:0xf bank_mask:0xf
	v_fmac_f32_dpp v233, v49, v225 row_ror:15 row_mask:0xf bank_mask:0xf
	v_fmac_f32_dpp v234, v38, v226 row_ror:15 row_mask:0xf bank_mask:0xf
	v_fmac_f32_dpp v235, v39, v227 row_ror:15 row_mask:0xf bank_mask:0xf
	v_fmac_f32_dpp v236, v40, v228 row_ror:15 row_mask:0xf bank_mask:0xf
	v_fmac_f32_dpp v237, v41, v229 row_ror:15 row_mask:0xf bank_mask:0xf
	v_pk_mul_f32 v[174:175], v[230:231], s[34:35]
	v_pk_mul_f32 v[176:177], v[232:233], s[34:35]
	v_exp_f32_e32 v174, v174
	v_exp_f32_e32 v175, v175
	v_exp_f32_e32 v176, v176
	v_exp_f32_e32 v177, v177
	v_pk_add_f32 v[174:175], v[174:175], s[36:37]
	v_pk_add_f32 v[176:177], v[176:177], s[36:37]
	v_rcp_f32_e32 v174, v174
	v_rcp_f32_e32 v175, v175
	v_rcp_f32_e32 v176, v176
	v_rcp_f32_e32 v177, v177
	v_pk_mul_f32 v[174:175], v[230:231], v[174:175]
	v_pk_mul_f32 v[176:177], v[232:233], v[176:177]
	v_pk_mul_f32 v[174:175], v[174:175], v[234:235]
	v_pk_mul_f32 v[176:177], v[176:177], v[236:237]
	v_cvt_pk_bf16_f32 v136, v174, v175
	v_cvt_pk_bf16_f32 v137, v176, v177
	v_add_u32_e32 v239, 0x2b000, v238
	global_store_dwordx4 v239, v[134:137], s[30:31]
	v_pk_fma_f32 v[230:231], v[46:47], v[118:119], v[106:107]
	v_pk_fma_f32 v[232:233], v[48:49], v[120:121], v[108:109]
	v_pk_fma_f32 v[234:235], v[38:39], v[114:115], v[98:99]
	v_pk_fma_f32 v[236:237], v[40:41], v[116:117], v[100:101]
	v_fmac_f32_dpp v230, v46, v126 row_shr:1 row_mask:0xf bank_mask:0xf
	v_fmac_f32_dpp v231, v47, v127 row_shr:1 row_mask:0xf bank_mask:0xf
	v_fmac_f32_dpp v232, v48, v128 row_shr:1 row_mask:0xf bank_mask:0xf
	v_fmac_f32_dpp v233, v49, v129 row_shr:1 row_mask:0xf bank_mask:0xf
	v_fmac_f32_dpp v234, v38, v122 row_shr:1 row_mask:0xf bank_mask:0xf
	v_fmac_f32_dpp v235, v39, v123 row_shr:1 row_mask:0xf bank_mask:0xf
	v_fmac_f32_dpp v236, v40, v124 row_shr:1 row_mask:0xf bank_mask:0xf
	v_fmac_f32_dpp v237, v41, v125 row_shr:1 row_mask:0xf bank_mask:0xf
	v_fmac_f32_dpp v230, v46, v110 row_shl:1 row_mask:0xf bank_mask:0xf
	v_fmac_f32_dpp v231, v47, v111 row_shl:1 row_mask:0xf bank_mask:0xf
	v_fmac_f32_dpp v232, v48, v112 row_shl:1 row_mask:0xf bank_mask:0xf
	v_fmac_f32_dpp v233, v49, v113 row_shl:1 row_mask:0xf bank_mask:0xf
	v_fmac_f32_dpp v234, v38, v102 row_shl:1 row_mask:0xf bank_mask:0xf
	v_fmac_f32_dpp v235, v39, v103 row_shl:1 row_mask:0xf bank_mask:0xf
	v_fmac_f32_dpp v236, v40, v104 row_shl:1 row_mask:0xf bank_mask:0xf
	v_fmac_f32_dpp v237, v41, v105 row_shl:1 row_mask:0xf bank_mask:0xf
	v_fmac_f32_dpp v230, v58, v214 row_ror:1 row_mask:0xf bank_mask:0xf
	v_fmac_f32_dpp v231, v59, v215 row_ror:1 row_mask:0xf bank_mask:0xf
	v_fmac_f32_dpp v232, v60, v216 row_ror:1 row_mask:0xf bank_mask:0xf
	v_fmac_f32_dpp v233, v61, v217 row_ror:1 row_mask:0xf bank_mask:0xf
	v_fmac_f32_dpp v234, v50, v218 row_ror:1 row_mask:0xf bank_mask:0xf
	v_fmac_f32_dpp v235, v51, v219 row_ror:1 row_mask:0xf bank_mask:0xf
	v_fmac_f32_dpp v236, v52, v220 row_ror:1 row_mask:0xf bank_mask:0xf
	v_fmac_f32_dpp v237, v53, v221 row_ror:1 row_mask:0xf bank_mask:0xf
	v_fmac_f32_dpp v230, v42, v222 row_ror:15 row_mask:0xf bank_mask:0xf
	v_fmac_f32_dpp v231, v43, v223 row_ror:15 row_mask:0xf bank_mask:0xf
	v_fmac_f32_dpp v232, v44, v224 row_ror:15 row_mask:0xf bank_mask:0xf
	v_fmac_f32_dpp v233, v45, v225 row_ror:15 row_mask:0xf bank_mask:0xf
	v_fmac_f32_dpp v234, v34, v226 row_ror:15 row_mask:0xf bank_mask:0xf
	v_fmac_f32_dpp v235, v35, v227 row_ror:15 row_mask:0xf bank_mask:0xf
	v_fmac_f32_dpp v236, v36, v228 row_ror:15 row_mask:0xf bank_mask:0xf
	v_fmac_f32_dpp v237, v37, v229 row_ror:15 row_mask:0xf bank_mask:0xf
	v_pk_mul_f32 v[174:175], v[230:231], s[34:35]
	v_pk_mul_f32 v[176:177], v[232:233], s[34:35]
	v_exp_f32_e32 v174, v174
	v_exp_f32_e32 v175, v175
	v_exp_f32_e32 v176, v176
	v_exp_f32_e32 v177, v177
	v_pk_add_f32 v[174:175], v[174:175], s[36:37]
	v_pk_add_f32 v[176:177], v[176:177], s[36:37]
	v_rcp_f32_e32 v174, v174
	v_rcp_f32_e32 v175, v175
	v_rcp_f32_e32 v176, v176
	v_rcp_f32_e32 v177, v177
	v_pk_mul_f32 v[174:175], v[230:231], v[174:175]
	v_pk_mul_f32 v[176:177], v[232:233], v[176:177]
	v_pk_mul_f32 v[174:175], v[174:175], v[234:235]
	v_pk_mul_f32 v[176:177], v[176:177], v[236:237]
	v_cvt_pk_bf16_f32 v140, v174, v175
; __device__ __forceinline__ unsigned cvt_pk_bf16(float lo, float hi) { unsigned r; asm volatile("v_cvt_pk_bf16_f32 %0, %1, %2" : "=v"(r) : "v"(lo), "v"(hi)); return r; }
; __device__ __forceinline__ float sigmoid_f(float x) { return fast_rcp(1.0f + fast_exp2(-1.4426950409f * x)); }
;     __device__ __forceinline__ void operator()(f32x4 (&acc)[2][2][4][2], const Unit& u, int wr, int wc, int fr, int fq) const {
;     ...
;                 for (int m = 0; m < 4; ++m) {
;                     f32x4 cv[2];
; #pragma unroll
;                     for (int bj = 0; bj < 2; ++bj) {
;                         const f32x4 cur = acc[ai][bj][m][n], lo = acc[ai][bj][m > 0 ? m - 1 : 0][n], hi = acc[ai][bj][m < 3 ? m + 1 : 3][n];
;                         f32x4 pv, nv;
; #pragma unroll
;                         for (int idx = 0; idx < 4; ++idx) {
;                             const float y = (fr == 15) ? lo[idx] : cur[idx], z = (fr == 0) ? hi[idx] : cur[idx];
;                             pv[idx] = __int_as_float(__builtin_amdgcn_update_dpp(0, __float_as_int(y), 0x121, 0xf, 0xf, false));
;                             nv[idx] = __int_as_float(__builtin_amdgcn_update_dpp(0, __float_as_int(z), 0x12f, 0xf, 0xf, false));
;                         }
;                         cv[bj] = kc[bj][0] * pv + kc[bj][1] * cur + kc[bj][2] * nv + bc[bj];
;                     }
;                     const int row = row0 + ai * HALF + m * 16;
;                     const bool edge = (m == 0 && fr == 0) || (m == 3 && fr == 15);
;                     if (!edge) { const f32x4 gt = cv[0], vl = cv[1];
;                         u32x2 w; w.x = cvt_pk_bf16(gt[0] * sigmoid_f(gt[0]) * vl[0], gt[1] * sigmoid_f(gt[1]) * vl[1]); w.y = cvt_pk_bf16(gt[2] * sigmoid_f(gt[2]) * vl[2], gt[3] * sigmoid_f(gt[3]) * vl[3]);
;                         *(u32x2*)(ACT + (size_t)row * FF + j4) = w; }
	v_cvt_pk_bf16_f32 v141, v176, v177
	v_add_u32_e32 v239, 0x56000, v238
	global_store_dwordx4 v239, v[138:141], s[30:31]
	v_pk_fma_f32 v[230:231], v[42:43], v[118:119], v[106:107]
	v_pk_fma_f32 v[232:233], v[44:45], v[120:121], v[108:109]
	v_pk_fma_f32 v[234:235], v[34:35], v[114:115], v[98:99]
	v_pk_fma_f32 v[236:237], v[36:37], v[116:117], v[100:101]
	v_fmac_f32_dpp v230, v42, v126 row_shr:1 row_mask:0xf bank_mask:0xf
	v_fmac_f32_dpp v231, v43, v127 row_shr:1 row_mask:0xf bank_mask:0xf
	v_fmac_f32_dpp v232, v44, v128 row_shr:1 row_mask:0xf bank_mask:0xf
	v_fmac_f32_dpp v233, v45, v129 row_shr:1 row_mask:0xf bank_mask:0xf
	v_fmac_f32_dpp v234, v34, v122 row_shr:1 row_mask:0xf bank_mask:0xf
	v_fmac_f32_dpp v235, v35, v123 row_shr:1 row_mask:0xf bank_mask:0xf
	v_fmac_f32_dpp v236, v36, v124 row_shr:1 row_mask:0xf bank_mask:0xf
	v_fmac_f32_dpp v237, v37, v125 row_shr:1 row_mask:0xf bank_mask:0xf
	v_fmac_f32_dpp v230, v42, v110 row_shl:1 row_mask:0xf bank_mask:0xf
	v_fmac_f32_dpp v231, v43, v111 row_shl:1 row_mask:0xf bank_mask:0xf
	v_fmac_f32_dpp v232, v44, v112 row_shl:1 row_mask:0xf bank_mask:0xf
	v_fmac_f32_dpp v233, v45, v113 row_shl:1 row_mask:0xf bank_mask:0xf
	v_fmac_f32_dpp v234, v34, v102 row_shl:1 row_mask:0xf bank_mask:0xf
	v_fmac_f32_dpp v235, v35, v103 row_shl:1 row_mask:0xf bank_mask:0xf
	v_fmac_f32_dpp v236, v36, v104 row_shl:1 row_mask:0xf bank_mask:0xf
	v_fmac_f32_dpp v237, v37, v105 row_shl:1 row_mask:0xf bank_mask:0xf
	v_fmac_f32_dpp v230, v46, v214 row_ror:1 row_mask:0xf bank_mask:0xf
	v_fmac_f32_dpp v231, v47, v215 row_ror:1 row_mask:0xf bank_mask:0xf
	v_fmac_f32_dpp v232, v48, v216 row_ror:1 row_mask:0xf bank_mask:0xf
	v_fmac_f32_dpp v233, v49, v217 row_ror:1 row_mask:0xf bank_mask:0xf
	v_fmac_f32_dpp v234, v38, v218 row_ror:1 row_mask:0xf bank_mask:0xf
	v_fmac_f32_dpp v235, v39, v219 row_ror:1 row_mask:0xf bank_mask:0xf
	v_fmac_f32_dpp v236, v40, v220 row_ror:1 row_mask:0xf bank_mask:0xf
	v_fmac_f32_dpp v237, v41, v221 row_ror:1 row_mask:0xf bank_mask:0xf
	v_pk_mul_f32 v[174:175], v[230:231], s[34:35]
	v_pk_mul_f32 v[176:177], v[232:233], s[34:35]
	v_exp_f32_e32 v174, v174
	v_exp_f32_e32 v175, v175
	v_exp_f32_e32 v176, v176
	v_exp_f32_e32 v177, v177
	v_pk_add_f32 v[174:175], v[174:175], s[36:37]
	v_pk_add_f32 v[176:177], v[176:177], s[36:37]
	v_rcp_f32_e32 v174, v174
	v_rcp_f32_e32 v175, v175
	v_rcp_f32_e32 v176, v176
	v_rcp_f32_e32 v177, v177
	v_pk_mul_f32 v[174:175], v[230:231], v[174:175]
	v_pk_mul_f32 v[176:177], v[232:233], v[176:177]
	v_pk_mul_f32 v[174:175], v[174:175], v[234:235]
	v_pk_mul_f32 v[176:177], v[176:177], v[236:237]
	v_cvt_pk_bf16_f32 v144, v174, v175
	v_cvt_pk_bf16_f32 v145, v176, v177
	v_add_u32_e32 v239, 0x81000, v238
	s_and_saveexec_b64 s[16:17], s[40:41]
	global_store_dwordx4 v239, v[142:145], s[30:31]
	s_or_b64 exec, exec, s[16:17]
	v_pk_fma_f32 v[230:231], v[30:31], v[118:119], v[106:107]
	v_pk_fma_f32 v[232:233], v[32:33], v[120:121], v[108:109]
	v_pk_fma_f32 v[234:235], v[22:23], v[114:115], v[98:99]
	v_pk_fma_f32 v[236:237], v[24:25], v[116:117], v[100:101]
	v_fmac_f32_dpp v230, v30, v126 row_shr:1 row_mask:0xf bank_mask:0xf
	v_fmac_f32_dpp v231, v31, v127 row_shr:1 row_mask:0xf bank_mask:0xf
	v_fmac_f32_dpp v232, v32, v128 row_shr:1 row_mask:0xf bank_mask:0xf
	v_fmac_f32_dpp v233, v33, v129 row_shr:1 row_mask:0xf bank_mask:0xf
	v_fmac_f32_dpp v234, v22, v122 row_shr:1 row_mask:0xf bank_mask:0xf
	v_fmac_f32_dpp v235, v23, v123 row_shr:1 row_mask:0xf bank_mask:0xf
	v_fmac_f32_dpp v236, v24, v124 row_shr:1 row_mask:0xf bank_mask:0xf
	v_fmac_f32_dpp v237, v25, v125 row_shr:1 row_mask:0xf bank_mask:0xf
	v_fmac_f32_dpp v230, v30, v110 row_shl:1 row_mask:0xf bank_mask:0xf
	v_fmac_f32_dpp v231, v31, v111 row_shl:1 row_mask:0xf bank_mask:0xf
	v_fmac_f32_dpp v232, v32, v112 row_shl:1 row_mask:0xf bank_mask:0xf
	v_fmac_f32_dpp v233, v33, v113 row_shl:1 row_mask:0xf bank_mask:0xf
	v_fmac_f32_dpp v234, v22, v102 row_shl:1 row_mask:0xf bank_mask:0xf
	v_fmac_f32_dpp v235, v23, v103 row_shl:1 row_mask:0xf bank_mask:0xf
	v_fmac_f32_dpp v236, v24, v104 row_shl:1 row_mask:0xf bank_mask:0xf
	v_fmac_f32_dpp v237, v25, v105 row_shl:1 row_mask:0xf bank_mask:0xf
	v_fmac_f32_dpp v230, v26, v222 row_ror:15 row_mask:0xf bank_mask:0xf
	v_fmac_f32_dpp v231, v27, v223 row_ror:15 row_mask:0xf bank_mask:0xf
	v_fmac_f32_dpp v232, v28, v224 row_ror:15 row_mask:0xf bank_mask:0xf
	v_fmac_f32_dpp v233, v29, v225 row_ror:15 row_mask:0xf bank_mask:0xf
	v_fmac_f32_dpp v234, v18, v226 row_ror:15 row_mask:0xf bank_mask:0xf
	v_fmac_f32_dpp v235, v19, v227 row_ror:15 row_mask:0xf bank_mask:0xf
	v_fmac_f32_dpp v236, v20, v228 row_ror:15 row_mask:0xf bank_mask:0xf
	v_fmac_f32_dpp v237, v21, v229 row_ror:15 row_mask:0xf bank_mask:0xf
	v_pk_mul_f32 v[174:175], v[230:231], s[34:35]
	v_pk_mul_f32 v[176:177], v[232:233], s[34:35]
	v_exp_f32_e32 v174, v174
	v_exp_f32_e32 v175, v175
	v_exp_f32_e32 v176, v176
	v_exp_f32_e32 v177, v177
	v_pk_add_f32 v[174:175], v[174:175], s[36:37]
	v_pk_add_f32 v[176:177], v[176:177], s[36:37]
	v_rcp_f32_e32 v174, v174
	v_rcp_f32_e32 v175, v175
	v_rcp_f32_e32 v176, v176
	v_rcp_f32_e32 v177, v177
	v_pk_mul_f32 v[174:175], v[230:231], v[174:175]
	v_pk_mul_f32 v[176:177], v[232:233], v[176:177]
	v_pk_mul_f32 v[174:175], v[174:175], v[234:235]
	v_pk_mul_f32 v[176:177], v[176:177], v[236:237]
	v_cvt_pk_bf16_f32 v180, v174, v175
	v_cvt_pk_bf16_f32 v181, v176, v177
	v_add_u32_e32 v239, 0x158000, v238
	s_and_saveexec_b64 s[16:17], s[44:45]
	global_store_dwordx4 v239, v[178:181], s[30:31]
	s_or_b64 exec, exec, s[16:17]
	v_pk_fma_f32 v[230:231], v[26:27], v[118:119], v[106:107]
	v_pk_fma_f32 v[232:233], v[28:29], v[120:121], v[108:109]
; __device__ __forceinline__ unsigned cvt_pk_bf16(float lo, float hi) { unsigned r; asm volatile("v_cvt_pk_bf16_f32 %0, %1, %2" : "=v"(r) : "v"(lo), "v"(hi)); return r; }
; __device__ __forceinline__ float sigmoid_f(float x) { return fast_rcp(1.0f + fast_exp2(-1.4426950409f * x)); }
;     __device__ __forceinline__ void operator()(f32x4 (&acc)[2][2][4][2], const Unit& u, int wr, int wc, int fr, int fq) const {
;     ...
;                 for (int m = 0; m < 4; ++m) {
;                     f32x4 cv[2];
; #pragma unroll
;                     for (int bj = 0; bj < 2; ++bj) {
;                         const f32x4 cur = acc[ai][bj][m][n], lo = acc[ai][bj][m > 0 ? m - 1 : 0][n], hi = acc[ai][bj][m < 3 ? m + 1 : 3][n];
;                         f32x4 pv, nv;
; #pragma unroll
;                         for (int idx = 0; idx < 4; ++idx) {
;                             const float y = (fr == 15) ? lo[idx] : cur[idx], z = (fr == 0) ? hi[idx] : cur[idx];
;                             pv[idx] = __int_as_float(__builtin_amdgcn_update_dpp(0, __float_as_int(y), 0x121, 0xf, 0xf, false));
;                             nv[idx] = __int_as_float(__builtin_amdgcn_update_dpp(0, __float_as_int(z), 0x12f, 0xf, 0xf, false));
;                         }
;                         cv[bj] = kc[bj][0] * pv + kc[bj][1] * cur + kc[bj][2] * nv + bc[bj];
;                     }
;                     const int row = row0 + ai * HALF + m * 16;
;                     const bool edge = (m == 0 && fr == 0) || (m == 3 && fr == 15);
;                     if (!edge) { const f32x4 gt = cv[0], vl = cv[1];
;                         u32x2 w; w.x = cvt_pk_bf16(gt[0] * sigmoid_f(gt[0]) * vl[0], gt[1] * sigmoid_f(gt[1]) * vl[1]); w.y = cvt_pk_bf16(gt[2] * sigmoid_f(gt[2]) * vl[2], gt[3] * sigmoid_f(gt[3]) * vl[3]);
;                         *(u32x2*)(ACT + (size_t)row * FF + j4) = w; }
	v_pk_fma_f32 v[234:235], v[18:19], v[114:115], v[98:99]
	v_pk_fma_f32 v[236:237], v[20:21], v[116:117], v[100:101]
	v_fmac_f32_dpp v230, v26, v126 row_shr:1 row_mask:0xf bank_mask:0xf
	v_fmac_f32_dpp v231, v27, v127 row_shr:1 row_mask:0xf bank_mask:0xf
	v_fmac_f32_dpp v232, v28, v128 row_shr:1 row_mask:0xf bank_mask:0xf
	v_fmac_f32_dpp v233, v29, v129 row_shr:1 row_mask:0xf bank_mask:0xf
	v_fmac_f32_dpp v234, v18, v122 row_shr:1 row_mask:0xf bank_mask:0xf
	v_fmac_f32_dpp v235, v19, v123 row_shr:1 row_mask:0xf bank_mask:0xf
	v_fmac_f32_dpp v236, v20, v124 row_shr:1 row_mask:0xf bank_mask:0xf
	v_fmac_f32_dpp v237, v21, v125 row_shr:1 row_mask:0xf bank_mask:0xf
	v_fmac_f32_dpp v230, v26, v110 row_shl:1 row_mask:0xf bank_mask:0xf
	v_fmac_f32_dpp v231, v27, v111 row_shl:1 row_mask:0xf bank_mask:0xf
	v_fmac_f32_dpp v232, v28, v112 row_shl:1 row_mask:0xf bank_mask:0xf
	v_fmac_f32_dpp v233, v29, v113 row_shl:1 row_mask:0xf bank_mask:0xf
	v_fmac_f32_dpp v234, v18, v102 row_shl:1 row_mask:0xf bank_mask:0xf
	v_fmac_f32_dpp v235, v19, v103 row_shl:1 row_mask:0xf bank_mask:0xf
	v_fmac_f32_dpp v236, v20, v104 row_shl:1 row_mask:0xf bank_mask:0xf
	v_fmac_f32_dpp v237, v21, v105 row_shl:1 row_mask:0xf bank_mask:0xf
	v_fmac_f32_dpp v230, v30, v214 row_ror:1 row_mask:0xf bank_mask:0xf
	v_fmac_f32_dpp v231, v31, v215 row_ror:1 row_mask:0xf bank_mask:0xf
	v_fmac_f32_dpp v232, v32, v216 row_ror:1 row_mask:0xf bank_mask:0xf
	v_fmac_f32_dpp v233, v33, v217 row_ror:1 row_mask:0xf bank_mask:0xf
	v_fmac_f32_dpp v234, v22, v218 row_ror:1 row_mask:0xf bank_mask:0xf
	v_fmac_f32_dpp v235, v23, v219 row_ror:1 row_mask:0xf bank_mask:0xf
	v_fmac_f32_dpp v236, v24, v220 row_ror:1 row_mask:0xf bank_mask:0xf
	v_fmac_f32_dpp v237, v25, v221 row_ror:1 row_mask:0xf bank_mask:0xf
	v_fmac_f32_dpp v230, v14, v222 row_ror:15 row_mask:0xf bank_mask:0xf
	v_fmac_f32_dpp v231, v15, v223 row_ror:15 row_mask:0xf bank_mask:0xf
	v_fmac_f32_dpp v232, v16, v224 row_ror:15 row_mask:0xf bank_mask:0xf
	v_fmac_f32_dpp v233, v17, v225 row_ror:15 row_mask:0xf bank_mask:0xf
	v_fmac_f32_dpp v234, v6, v226 row_ror:15 row_mask:0xf bank_mask:0xf
	v_fmac_f32_dpp v235, v7, v227 row_ror:15 row_mask:0xf bank_mask:0xf
	v_fmac_f32_dpp v236, v8, v228 row_ror:15 row_mask:0xf bank_mask:0xf
	v_fmac_f32_dpp v237, v9, v229 row_ror:15 row_mask:0xf bank_mask:0xf
	v_pk_mul_f32 v[174:175], v[230:231], s[34:35]
	v_pk_mul_f32 v[176:177], v[232:233], s[34:35]
	v_exp_f32_e32 v174, v174
	v_exp_f32_e32 v175, v175
	v_exp_f32_e32 v176, v176
	v_exp_f32_e32 v177, v177
	v_pk_add_f32 v[174:175], v[174:175], s[36:37]
	v_pk_add_f32 v[176:177], v[176:177], s[36:37]
	v_rcp_f32_e32 v174, v174
	v_rcp_f32_e32 v175, v175
	v_rcp_f32_e32 v176, v176
	v_rcp_f32_e32 v177, v177
	v_pk_mul_f32 v[174:175], v[230:231], v[174:175]
	v_pk_mul_f32 v[176:177], v[232:233], v[176:177]
	v_pk_mul_f32 v[174:175], v[174:175], v[234:235]
	v_pk_mul_f32 v[176:177], v[176:177], v[236:237]
	v_cvt_pk_bf16_f32 v96, v174, v175
	v_cvt_pk_bf16_f32 v97, v176, v177
	v_add_u32_e32 v239, 0x183000, v238
	global_store_dwordx4 v239, v[94:97], s[30:31]
	v_pk_fma_f32 v[230:231], v[14:15], v[118:119], v[106:107]
	v_pk_fma_f32 v[232:233], v[16:17], v[120:121], v[108:109]
	v_pk_fma_f32 v[234:235], v[6:7], v[114:115], v[98:99]
	v_pk_fma_f32 v[236:237], v[8:9], v[116:117], v[100:101]
	v_fmac_f32_dpp v230, v14, v126 row_shr:1 row_mask:0xf bank_mask:0xf
	v_fmac_f32_dpp v231, v15, v127 row_shr:1 row_mask:0xf bank_mask:0xf
	v_fmac_f32_dpp v232, v16, v128 row_shr:1 row_mask:0xf bank_mask:0xf
	v_fmac_f32_dpp v233, v17, v129 row_shr:1 row_mask:0xf bank_mask:0xf
	v_fmac_f32_dpp v234, v6, v122 row_shr:1 row_mask:0xf bank_mask:0xf
	v_fmac_f32_dpp v235, v7, v123 row_shr:1 row_mask:0xf bank_mask:0xf
	v_fmac_f32_dpp v236, v8, v124 row_shr:1 row_mask:0xf bank_mask:0xf
	v_fmac_f32_dpp v237, v9, v125 row_shr:1 row_mask:0xf bank_mask:0xf
	v_fmac_f32_dpp v230, v14, v110 row_shl:1 row_mask:0xf bank_mask:0xf
	v_fmac_f32_dpp v231, v15, v111 row_shl:1 row_mask:0xf bank_mask:0xf
	v_fmac_f32_dpp v232, v16, v112 row_shl:1 row_mask:0xf bank_mask:0xf
	v_fmac_f32_dpp v233, v17, v113 row_shl:1 row_mask:0xf bank_mask:0xf
	v_fmac_f32_dpp v234, v6, v102 row_shl:1 row_mask:0xf bank_mask:0xf
	v_fmac_f32_dpp v235, v7, v103 row_shl:1 row_mask:0xf bank_mask:0xf
	v_fmac_f32_dpp v236, v8, v104 row_shl:1 row_mask:0xf bank_mask:0xf
	v_fmac_f32_dpp v237, v9, v105 row_shl:1 row_mask:0xf bank_mask:0xf
	v_fmac_f32_dpp v230, v26, v214 row_ror:1 row_mask:0xf bank_mask:0xf
	v_fmac_f32_dpp v231, v27, v215 row_ror:1 row_mask:0xf bank_mask:0xf
; __device__ __forceinline__ unsigned cvt_pk_bf16(float lo, float hi) { unsigned r; asm volatile("v_cvt_pk_bf16_f32 %0, %1, %2" : "=v"(r) : "v"(lo), "v"(hi)); return r; }
; __device__ __forceinline__ float sigmoid_f(float x) { return fast_rcp(1.0f + fast_exp2(-1.4426950409f * x)); }
;     __device__ __forceinline__ void operator()(f32x4 (&acc)[2][2][4][2], const Unit& u, int wr, int wc, int fr, int fq) const {
;     ...
;                 for (int m = 0; m < 4; ++m) {
;                     f32x4 cv[2];
; #pragma unroll
;                     for (int bj = 0; bj < 2; ++bj) {
;                         const f32x4 cur = acc[ai][bj][m][n], lo = acc[ai][bj][m > 0 ? m - 1 : 0][n], hi = acc[ai][bj][m < 3 ? m + 1 : 3][n];
;                         f32x4 pv, nv;
; #pragma unroll
;                         for (int idx = 0; idx < 4; ++idx) {
;                             const float y = (fr == 15) ? lo[idx] : cur[idx], z = (fr == 0) ? hi[idx] : cur[idx];
;                             pv[idx] = __int_as_float(__builtin_amdgcn_update_dpp(0, __float_as_int(y), 0x121, 0xf, 0xf, false));
;                             nv[idx] = __int_as_float(__builtin_amdgcn_update_dpp(0, __float_as_int(z), 0x12f, 0xf, 0xf, false));
;                         }
;                         cv[bj] = kc[bj][0] * pv + kc[bj][1] * cur + kc[bj][2] * nv + bc[bj];
;                     }
;                     const int row = row0 + ai * HALF + m * 16;
;                     const bool edge = (m == 0 && fr == 0) || (m == 3 && fr == 15);
;                     if (!edge) { const f32x4 gt = cv[0], vl = cv[1];
;                         u32x2 w; w.x = cvt_pk_bf16(gt[0] * sigmoid_f(gt[0]) * vl[0], gt[1] * sigmoid_f(gt[1]) * vl[1]); w.y = cvt_pk_bf16(gt[2] * sigmoid_f(gt[2]) * vl[2], gt[3] * sigmoid_f(gt[3]) * vl[3]);
;                         *(u32x2*)(ACT + (size_t)row * FF + j4) = w; }
	v_fmac_f32_dpp v232, v28, v216 row_ror:1 row_mask:0xf bank_mask:0xf
	v_fmac_f32_dpp v233, v29, v217 row_ror:1 row_mask:0xf bank_mask:0xf
	v_fmac_f32_dpp v234, v18, v218 row_ror:1 row_mask:0xf bank_mask:0xf
	v_fmac_f32_dpp v235, v19, v219 row_ror:1 row_mask:0xf bank_mask:0xf
	v_fmac_f32_dpp v236, v20, v220 row_ror:1 row_mask:0xf bank_mask:0xf
	v_fmac_f32_dpp v237, v21, v221 row_ror:1 row_mask:0xf bank_mask:0xf
	v_fmac_f32_dpp v230, v10, v222 row_ror:15 row_mask:0xf bank_mask:0xf
	v_fmac_f32_dpp v231, v11, v223 row_ror:15 row_mask:0xf bank_mask:0xf
	v_fmac_f32_dpp v232, v12, v224 row_ror:15 row_mask:0xf bank_mask:0xf
	v_fmac_f32_dpp v233, v13, v225 row_ror:15 row_mask:0xf bank_mask:0xf
	v_fmac_f32_dpp v234, v2, v226 row_ror:15 row_mask:0xf bank_mask:0xf
	v_fmac_f32_dpp v235, v3, v227 row_ror:15 row_mask:0xf bank_mask:0xf
	v_fmac_f32_dpp v236, v4, v228 row_ror:15 row_mask:0xf bank_mask:0xf
	v_fmac_f32_dpp v237, v5, v229 row_ror:15 row_mask:0xf bank_mask:0xf
	v_pk_mul_f32 v[174:175], v[230:231], s[34:35]
	v_pk_mul_f32 v[176:177], v[232:233], s[34:35]
	v_exp_f32_e32 v174, v174
	v_exp_f32_e32 v175, v175
	v_exp_f32_e32 v176, v176
	v_exp_f32_e32 v177, v177
	v_pk_add_f32 v[174:175], v[174:175], s[36:37]
	v_pk_add_f32 v[176:177], v[176:177], s[36:37]
	v_rcp_f32_e32 v174, v174
	v_rcp_f32_e32 v175, v175
	v_rcp_f32_e32 v176, v176
	v_rcp_f32_e32 v177, v177
	v_pk_mul_f32 v[174:175], v[230:231], v[174:175]
	v_pk_mul_f32 v[176:177], v[232:233], v[176:177]
	v_pk_mul_f32 v[174:175], v[174:175], v[234:235]
	v_pk_mul_f32 v[176:177], v[176:177], v[236:237]
	v_cvt_pk_bf16_f32 v92, v174, v175
	v_cvt_pk_bf16_f32 v93, v176, v177
	v_add_u32_e32 v239, 0x1ae000, v238
	global_store_dwordx4 v239, v[90:93], s[30:31]
	v_pk_fma_f32 v[230:231], v[10:11], v[118:119], v[106:107]
	v_pk_fma_f32 v[232:233], v[12:13], v[120:121], v[108:109]
	v_pk_fma_f32 v[234:235], v[2:3], v[114:115], v[98:99]
	v_pk_fma_f32 v[236:237], v[4:5], v[116:117], v[100:101]
	v_fmac_f32_dpp v230, v10, v126 row_shr:1 row_mask:0xf bank_mask:0xf
	v_fmac_f32_dpp v231, v11, v127 row_shr:1 row_mask:0xf bank_mask:0xf
	v_fmac_f32_dpp v232, v12, v128 row_shr:1 row_mask:0xf bank_mask:0xf
	v_fmac_f32_dpp v233, v13, v129 row_shr:1 row_mask:0xf bank_mask:0xf
	v_fmac_f32_dpp v234, v2, v122 row_shr:1 row_mask:0xf bank_mask:0xf
	v_fmac_f32_dpp v235, v3, v123 row_shr:1 row_mask:0xf bank_mask:0xf
	v_fmac_f32_dpp v236, v4, v124 row_shr:1 row_mask:0xf bank_mask:0xf
	v_fmac_f32_dpp v237, v5, v125 row_shr:1 row_mask:0xf bank_mask:0xf
	v_fmac_f32_dpp v230, v10, v110 row_shl:1 row_mask:0xf bank_mask:0xf
	v_fmac_f32_dpp v231, v11, v111 row_shl:1 row_mask:0xf bank_mask:0xf
	v_fmac_f32_dpp v232, v12, v112 row_shl:1 row_mask:0xf bank_mask:0xf
	v_fmac_f32_dpp v233, v13, v113 row_shl:1 row_mask:0xf bank_mask:0xf
	v_fmac_f32_dpp v234, v2, v102 row_shl:1 row_mask:0xf bank_mask:0xf
	v_fmac_f32_dpp v235, v3, v103 row_shl:1 row_mask:0xf bank_mask:0xf
	v_fmac_f32_dpp v236, v4, v104 row_shl:1 row_mask:0xf bank_mask:0xf
	v_fmac_f32_dpp v237, v5, v105 row_shl:1 row_mask:0xf bank_mask:0xf
	v_fmac_f32_dpp v230, v14, v214 row_ror:1 row_mask:0xf bank_mask:0xf
	v_fmac_f32_dpp v231, v15, v215 row_ror:1 row_mask:0xf bank_mask:0xf
	v_fmac_f32_dpp v232, v16, v216 row_ror:1 row_mask:0xf bank_mask:0xf
	v_fmac_f32_dpp v233, v17, v217 row_ror:1 row_mask:0xf bank_mask:0xf
	v_fmac_f32_dpp v234, v6, v218 row_ror:1 row_mask:0xf bank_mask:0xf
	v_fmac_f32_dpp v235, v7, v219 row_ror:1 row_mask:0xf bank_mask:0xf
	v_fmac_f32_dpp v236, v8, v220 row_ror:1 row_mask:0xf bank_mask:0xf
	v_fmac_f32_dpp v237, v9, v221 row_ror:1 row_mask:0xf bank_mask:0xf
	v_pk_mul_f32 v[174:175], v[230:231], s[34:35]
	v_pk_mul_f32 v[176:177], v[232:233], s[34:35]
	v_exp_f32_e32 v174, v174
	v_exp_f32_e32 v175, v175
	v_exp_f32_e32 v176, v176
	v_exp_f32_e32 v177, v177
	v_pk_add_f32 v[174:175], v[174:175], s[36:37]
	v_pk_add_f32 v[176:177], v[176:177], s[36:37]
	v_rcp_f32_e32 v174, v174
	v_rcp_f32_e32 v175, v175
	v_rcp_f32_e32 v176, v176
	v_rcp_f32_e32 v177, v177
	v_pk_mul_f32 v[174:175], v[230:231], v[174:175]
	v_pk_mul_f32 v[176:177], v[232:233], v[176:177]
	v_pk_mul_f32 v[174:175], v[174:175], v[234:235]
	v_pk_mul_f32 v[176:177], v[176:177], v[236:237]
	v_cvt_pk_bf16_f32 v80, v174, v175
	v_cvt_pk_bf16_f32 v81, v176, v177
	v_add_u32_e32 v239, 0x1d9000, v238
	s_and_saveexec_b64 s[16:17], s[40:41]
	global_store_dwordx4 v239, v[78:81], s[30:31]
	s_or_b64 exec, exec, s[16:17]
	s_movk_i32 s94, 0x1000
	s_movk_i32 s95, 0x3000
	s_and_b64 vcc, exec, s[50:51]
	s_mov_b64 s[12:13], -1
	s_cbranch_vccnz .LBB0_746
